# K-loops: buffer-1 LDS fragment read bases kept in two spare VGPRs instead of being recomputed by VALU in every load segment
# baseline (speedup 1.0000x reference)
; template <class Epi, class Sched, bool ALIGN_EPI = false, bool SP2 = false, bool KSEG = false>
; __device__ __forceinline__ void gemm_phase(PG8_LAS unsigned char* lds, const Gemm g, const Sched& S, const Epi& E) {
;     ...
;         const bool has_next = S.next(ui + 1, nxt);
;         const char* nA = has_next ? (const char*)g.A + (size_t)nxt.pm * tstep : cA; const char* nB = has_next ? (const char*)g.Bt + (size_t)nxt.pn * tstep : cB;
;         for (int t = 0; t < nt; t += 2) {
;             const bool last = (t == nt - 2);
;             const char* a1 = cA + (size_t)(t + 1) * kstep;
;             const char* a2 = last ? nA : cA + (size_t)(t + 2) * kstep; const char* b2 = last ? nB : cB + (size_t)(t + 2) * kstep;
;             const char* a3 = a2 + kstep; const char* b3 = b2 + kstep;
;     ...
; #pragma unroll
;         for (int a = 0; a < 2; ++a)
; #pragma unroll
;             for (int b = 0; b < 2; ++b)
; #pragma unroll
;                 for (int m = 0; m < 4; ++m)
; #pragma unroll
;                     for (int n = 0; n < 2; ++n) acc[a][b][m][n] = (f32x4){0.f, 0.f, 0.f, 0.f};
;         cur = nxt; cA = nA; cB = nB; ++ui;
.LBB0_119:
	s_ashr_i32 s21, s20, 31
	s_lshl_b64 s[22:23], s[20:21], 20
	s_add_u32 s22, s74, s22
	s_addc_u32 s23, s75, s23
	s_and_b64 s[24:25], s[2:3], exec
	s_cselect_b32 s21, s23, s29
	s_cselect_b32 s64, s22, s28
	s_ashr_i32 s19, s18, 31
	s_lshl_b64 s[24:25], s[18:19], 20
	s_add_u32 s24, s8, s24
	s_addc_u32 s25, s9, s25
	s_and_b64 s[42:43], s[2:3], exec
	s_cselect_b32 s19, s25, s31
	s_cselect_b32 s65, s24, s30
	s_add_u32 s28, s28, 0x80080
	s_addc_u32 s29, s29, 0
	s_add_u32 s66, s30, 0x100
	v_mov_b32_e32 v2, 0
	s_addc_u32 s67, s31, 0
	s_mov_b32 s80, -2
	v_mov_b32_e32 v3, v2
	v_mov_b32_e32 v4, v2
	v_mov_b32_e32 v5, v2
	v_mov_b32_e32 v6, v2
	v_mov_b32_e32 v7, v2
	v_mov_b32_e32 v8, v2
	v_mov_b32_e32 v9, v2
	s_waitcnt vmcnt(0)
	v_mov_b32_e32 v18, v2
	v_mov_b32_e32 v19, v2
	v_mov_b32_e32 v20, v2
	v_mov_b32_e32 v21, v2
	v_mov_b32_e32 v22, v2
	v_mov_b32_e32 v23, v2
	v_mov_b32_e32 v24, v2
	v_mov_b32_e32 v25, v2
	v_mov_b32_e32 v34, v2
	v_mov_b32_e32 v35, v2
	v_mov_b32_e32 v36, v2
	v_mov_b32_e32 v37, v2
	v_mov_b32_e32 v38, v2
	s_waitcnt lgkmcnt(0)
	v_mov_b32_e32 v39, v2
	v_mov_b32_e32 v40, v2
	v_mov_b32_e32 v41, v2
	v_mov_b32_e32 v50, v2
	v_mov_b32_e32 v51, v2
	v_mov_b32_e32 v52, v2
	v_mov_b32_e32 v53, v2
	v_mov_b32_e32 v54, v2
	v_mov_b32_e32 v55, v2
	v_mov_b32_e32 v56, v2
	v_mov_b32_e32 v57, v2
	v_mov_b32_e32 v10, v2
	v_mov_b32_e32 v11, v2
	v_mov_b32_e32 v12, v2
	v_mov_b32_e32 v13, v2
	v_mov_b32_e32 v14, v2
	v_mov_b32_e32 v15, v2
	v_mov_b32_e32 v16, v2
	v_mov_b32_e32 v17, v2
	v_mov_b32_e32 v26, v2
	v_mov_b32_e32 v27, v2
	v_mov_b32_e32 v28, v2
	v_mov_b32_e32 v29, v2
	v_mov_b32_e32 v30, v2
	v_mov_b32_e32 v31, v2
	v_mov_b32_e32 v32, v2
	v_mov_b32_e32 v33, v2
	v_mov_b32_e32 v42, v2
	v_mov_b32_e32 v43, v2
	v_mov_b32_e32 v44, v2
	v_mov_b32_e32 v45, v2
	v_mov_b32_e32 v46, v2
	v_mov_b32_e32 v47, v2
	v_mov_b32_e32 v48, v2
	v_mov_b32_e32 v49, v2
	v_mov_b32_e32 v58, v2
	v_mov_b32_e32 v59, v2
	v_mov_b32_e32 v60, v2
	v_mov_b32_e32 v61, v2
	v_mov_b32_e32 v62, v2
	v_mov_b32_e32 v63, v2
	v_mov_b32_e32 v64, v2
	v_mov_b32_e32 v65, v2
	v_mov_b32_e32 v66, v2
	v_mov_b32_e32 v67, v2
	v_mov_b32_e32 v68, v2
	v_mov_b32_e32 v69, v2
	v_mov_b32_e32 v70, v2
	v_mov_b32_e32 v71, v2
	v_mov_b32_e32 v72, v2
	v_mov_b32_e32 v73, v2
	v_mov_b32_e32 v82, v2
	v_mov_b32_e32 v83, v2
	v_mov_b32_e32 v84, v2
	v_mov_b32_e32 v85, v2
	v_mov_b32_e32 v86, v2
	v_mov_b32_e32 v87, v2
	v_mov_b32_e32 v88, v2
	v_mov_b32_e32 v89, v2
	v_mov_b32_e32 v98, v2
	v_mov_b32_e32 v99, v2
	v_mov_b32_e32 v100, v2
	v_mov_b32_e32 v101, v2
	v_mov_b32_e32 v102, v2
	v_mov_b32_e32 v103, v2
	v_mov_b32_e32 v104, v2
	v_mov_b32_e32 v105, v2
	v_mov_b32_e32 v114, v2
	v_mov_b32_e32 v115, v2
	v_mov_b32_e32 v116, v2
	v_mov_b32_e32 v117, v2
	v_mov_b32_e32 v118, v2
	v_mov_b32_e32 v119, v2
	v_mov_b32_e32 v120, v2
	v_mov_b32_e32 v121, v2
	v_mov_b32_e32 v74, v2
	v_mov_b32_e32 v75, v2
	v_mov_b32_e32 v76, v2
	v_mov_b32_e32 v77, v2
	v_mov_b32_e32 v78, v2
	v_mov_b32_e32 v79, v2
	v_mov_b32_e32 v80, v2
	v_mov_b32_e32 v81, v2
	v_mov_b32_e32 v90, v2
	v_mov_b32_e32 v91, v2
	v_mov_b32_e32 v92, v2
	v_mov_b32_e32 v93, v2
	v_mov_b32_e32 v94, v2
	v_mov_b32_e32 v95, v2
	v_mov_b32_e32 v96, v2
	v_mov_b32_e32 v97, v2
	v_mov_b32_e32 v106, v2
	v_mov_b32_e32 v107, v2
	v_mov_b32_e32 v108, v2
	v_mov_b32_e32 v109, v2
	v_mov_b32_e32 v110, v2
	v_mov_b32_e32 v111, v2
	v_mov_b32_e32 v112, v2
	v_mov_b32_e32 v113, v2
	v_mov_b32_e32 v122, v2
	v_mov_b32_e32 v123, v2
	v_mov_b32_e32 v124, v2
	v_mov_b32_e32 v125, v2
	v_mov_b32_e32 v126, v2
	v_mov_b32_e32 v127, v2
	v_mov_b32_e32 v128, v2
	v_mov_b32_e32 v129, v2
	s_add_u32 s30, s28, 0xfff80080
	s_addc_u32 s31, s29, -1
	s_cmp_eq_u32 s80, 28
	s_cselect_b32 s43, s21, s31
	s_cselect_b32 s42, s64, s30
	s_cselect_b32 s31, s19, s67
	s_cselect_b32 s30, s65, s66
	s_add_u32 s98, s28, 0xfff80000
	s_addc_u32 s99, s29, -1
	v_add_u32_e32 v250, 0x18000, v154
	v_add_u32_e32 v251, 0x1c000, v154
.LBB0_120:
	ds_read_b128 v[146:149], v156
	ds_read_b128 v[150:153], v156 offset:1024
	ds_read_b128 v[160:163], v156 offset:2048
	ds_read_b128 v[164:167], v156 offset:3072
	ds_read_b128 v[168:171], v157
	ds_read_b128 v[172:175], v157 offset:1024
	ds_read_b128 v[176:179], v157 offset:2048
	ds_read_b128 v[180:183], v157 offset:3072
	s_mov_b32 m0, s51
	v_lshl_add_u64 v[216:217], s[98:99], 0, v[136:137]
	global_load_lds_dwordx4 v[216:217], off
	s_mov_b32 m0, s58
	v_lshl_add_u64 v[216:217], s[98:99], 0, v[132:133]
	global_load_lds_dwordx4 v[216:217], off
	v_lshl_add_u64 v[216:217], s[28:29], 0, v[138:139]
	s_add_i32 m0, s27, 0xc000
	ds_read_b128 v[184:187], v158
	ds_read_b128 v[188:191], v158 offset:1024
	ds_read_b128 v[192:195], v158 offset:2048
	ds_read_b128 v[196:199], v158 offset:3072
	ds_read_b128 v[200:203], v158 offset:4096
	ds_read_b128 v[204:207], v158 offset:5120
	ds_read_b128 v[208:211], v158 offset:6144
	ds_read_b128 v[212:215], v158 offset:7168
	global_load_lds_dwordx4 v[216:217], off
	s_add_i32 m0, s27, 0xe000
	v_lshl_add_u64 v[216:217], s[28:29], 0, v[140:141]
	global_load_lds_dwordx4 v[216:217], off
	s_waitcnt vmcnt(8) lgkmcnt(0)
	s_barrier
; #define PG8_STAGE(bufoff, gbase, voff) do { _Pragma("unroll") for (int _i = 0; _i < 2; ++_i) \
;         __builtin_amdgcn_global_load_lds((const unsigned*)((const char*)(gbase) + (voff)[_i]), (PG8_LAS unsigned*)(lds + (bufoff) + ldsw + _i * 8192), 16, 0, 0); } while (0)
; #define PG8_LDA(dst, b, h) do { _Pragma("unroll") for (int m = 0; m < 4; ++m) _Pragma("unroll") for (int k = 0; k < 2; ++k) dst[m][k] = *(const PG8_LAS bf16x8*)(lds + PG8_SA(b, h) + aoff + m * 2048 + k * 1024); } while (0)
; #define PG8_LDB(dst, b, h) do { _Pragma("unroll") for (int n = 0; n < 2; ++n) _Pragma("unroll") for (int k = 0; k < 2; ++k) dst[n][k] = *(const PG8_LAS bf16x8*)(lds + PG8_SB(b, h) + boff + n * 2048 + k * 1024); } while (0)
; #define PG8_MMA(ai, bj, At, Bt) do { __builtin_amdgcn_s_setprio(1); _Pragma("unroll") for (int m = 0; m < 4; ++m) _Pragma("unroll") for (int n = 0; n < 2; ++n) _Pragma("unroll") for (int k = 0; k < 2; ++k) \
;         acc[ai][bj][m][n] = __builtin_amdgcn_mfma_f32_16x16x32_bf16(Bt[n][k], At[m][k], acc[ai][bj][m][n], 0, 0, 0); __builtin_amdgcn_s_setprio(0); } while (0)
; #define PG8_WAIT_V(n) asm volatile("s_waitcnt vmcnt(" #n ")" ::: "memory")
; #define PG8_WAIT_L(n) asm volatile("s_waitcnt lgkmcnt(" #n ")" ::: "memory")
; #define PG8_BAR __builtin_amdgcn_s_barrier()
; #define PG8_SCHED __builtin_amdgcn_sched_barrier(0)
; template <class Epi, class Sched, bool ALIGN_EPI = false, bool SP2 = false, bool KSEG = false>
; __device__ __forceinline__ void gemm_phase(PG8_LAS unsigned char* lds, const Gemm g, const Sched& S, const Epi& E) {
;     ...
;             PG8_LDB(B0, 0, 0); PG8_LDB(B1, 0, 1); PG8_SCHED; PG8_LDA(At, 0, 0); PG8_STAGE(PG8_SA(1, 1), a1 + hstep, voffA);
;             PG8_WAIT_V(8); PG8_WAIT_L(0); PG8_BAR; PG8_MMA(0, 0, At, B0); PG8_MMA(0, 1, At, B1); PG8_BAR; PG8_SCHED;
;             PG8_LDA(At, 0, 1); PG8_STAGE(PG8_SB(0, 0), b2, voffB); PG8_STAGE(PG8_SB(0, 1), b2 + hstep, voffB); PG8_STAGE(PG8_SA(0, 0), a2, voffA);
;             PG8_WAIT_V(8); PG8_WAIT_L(0); PG8_BAR; PG8_MMA(1, 0, At, B0); PG8_MMA(1, 1, At, B1); PG8_BAR; PG8_SCHED;
	s_setprio 1
	v_mfma_f32_16x16x32_bf16 v[126:129], v[146:149], v[184:187], v[126:129]
	v_mfma_f32_16x16x32_bf16 v[122:125], v[160:163], v[184:187], v[122:125]
	v_mfma_f32_16x16x32_bf16 v[110:113], v[146:149], v[192:195], v[110:113]
	v_mfma_f32_16x16x32_bf16 v[106:109], v[160:163], v[192:195], v[106:109]
	v_mfma_f32_16x16x32_bf16 v[94:97], v[146:149], v[200:203], v[94:97]
	v_mfma_f32_16x16x32_bf16 v[90:93], v[160:163], v[200:203], v[90:93]
	v_mfma_f32_16x16x32_bf16 v[78:81], v[146:149], v[208:211], v[78:81]
	v_mfma_f32_16x16x32_bf16 v[74:77], v[160:163], v[208:211], v[74:77]
	v_mfma_f32_16x16x32_bf16 v[126:129], v[150:153], v[188:191], v[126:129]
	v_mfma_f32_16x16x32_bf16 v[122:125], v[164:167], v[188:191], v[122:125]
	v_mfma_f32_16x16x32_bf16 v[110:113], v[150:153], v[196:199], v[110:113]
	v_mfma_f32_16x16x32_bf16 v[106:109], v[164:167], v[196:199], v[106:109]
	v_mfma_f32_16x16x32_bf16 v[94:97], v[150:153], v[204:207], v[94:97]
	v_mfma_f32_16x16x32_bf16 v[90:93], v[164:167], v[204:207], v[90:93]
	v_mfma_f32_16x16x32_bf16 v[78:81], v[150:153], v[212:215], v[78:81]
	v_mfma_f32_16x16x32_bf16 v[74:77], v[164:167], v[212:215], v[74:77]
	s_setprio 0
	s_setprio 1
	v_mfma_f32_16x16x32_bf16 v[118:121], v[168:171], v[184:187], v[118:121]
	v_mfma_f32_16x16x32_bf16 v[114:117], v[176:179], v[184:187], v[114:117]
	v_mfma_f32_16x16x32_bf16 v[102:105], v[168:171], v[192:195], v[102:105]
	v_mfma_f32_16x16x32_bf16 v[98:101], v[176:179], v[192:195], v[98:101]
	v_mfma_f32_16x16x32_bf16 v[86:89], v[168:171], v[200:203], v[86:89]
	v_mfma_f32_16x16x32_bf16 v[82:85], v[176:179], v[200:203], v[82:85]
	v_mfma_f32_16x16x32_bf16 v[70:73], v[168:171], v[208:211], v[70:73]
	v_mfma_f32_16x16x32_bf16 v[66:69], v[176:179], v[208:211], v[66:69]
	v_mfma_f32_16x16x32_bf16 v[118:121], v[172:175], v[188:191], v[118:121]
	v_mfma_f32_16x16x32_bf16 v[114:117], v[180:183], v[188:191], v[114:117]
	v_mfma_f32_16x16x32_bf16 v[102:105], v[172:175], v[196:199], v[102:105]
	v_mfma_f32_16x16x32_bf16 v[98:101], v[180:183], v[196:199], v[98:101]
	v_mfma_f32_16x16x32_bf16 v[86:89], v[172:175], v[204:207], v[86:89]
	v_mfma_f32_16x16x32_bf16 v[82:85], v[180:183], v[204:207], v[82:85]
	v_mfma_f32_16x16x32_bf16 v[70:73], v[172:175], v[212:215], v[70:73]
	v_mfma_f32_16x16x32_bf16 v[66:69], v[180:183], v[212:215], v[66:69]
	s_setprio 0
	s_barrier
	s_add_i32 s33, s60, s44
	v_lshl_add_u64 v[216:217], s[30:31], 0, v[134:135]
	s_mov_b32 m0, s33
	ds_read_b128 v[184:187], v158 offset:16384
	ds_read_b128 v[188:191], v158 offset:17408
	ds_read_b128 v[192:195], v158 offset:18432
	ds_read_b128 v[196:199], v158 offset:19456
	ds_read_b128 v[200:203], v158 offset:20480
	ds_read_b128 v[204:207], v158 offset:21504
	ds_read_b128 v[208:211], v158 offset:22528
	ds_read_b128 v[212:215], v158 offset:23552
	global_load_lds_dwordx4 v[216:217], off
	s_add_i32 m0, s33, 0x2000
	s_add_u32 s84, s30, 0x80000
	v_lshl_add_u64 v[218:219], s[30:31], 0, v[130:131]
	s_addc_u32 s85, s31, 0
	s_add_i32 s33, s61, s44
	global_load_lds_dwordx4 v[218:219], off
	s_mov_b32 m0, s33
	v_lshl_add_u64 v[220:221], s[84:85], 0, v[134:135]
	global_load_lds_dwordx4 v[220:221], off
	s_add_i32 m0, s33, 0x2000
	v_lshl_add_u64 v[220:221], s[84:85], 0, v[130:131]
	global_load_lds_dwordx4 v[220:221], off
	s_waitcnt vmcnt(6) lgkmcnt(0)
	s_barrier
	s_setprio 1
	v_mfma_f32_16x16x32_bf16 v[62:65], v[146:149], v[184:187], v[62:65]
	v_mfma_f32_16x16x32_bf16 v[58:61], v[160:163], v[184:187], v[58:61]
	v_mfma_f32_16x16x32_bf16 v[46:49], v[146:149], v[192:195], v[46:49]
	v_mfma_f32_16x16x32_bf16 v[42:45], v[160:163], v[192:195], v[42:45]
	v_mfma_f32_16x16x32_bf16 v[30:33], v[146:149], v[200:203], v[30:33]
	v_mfma_f32_16x16x32_bf16 v[26:29], v[160:163], v[200:203], v[26:29]
	v_mfma_f32_16x16x32_bf16 v[14:17], v[146:149], v[208:211], v[14:17]
	v_mfma_f32_16x16x32_bf16 v[10:13], v[160:163], v[208:211], v[10:13]
	v_mfma_f32_16x16x32_bf16 v[62:65], v[150:153], v[188:191], v[62:65]
	v_mfma_f32_16x16x32_bf16 v[58:61], v[164:167], v[188:191], v[58:61]
	v_mfma_f32_16x16x32_bf16 v[46:49], v[150:153], v[196:199], v[46:49]
	v_mfma_f32_16x16x32_bf16 v[42:45], v[164:167], v[196:199], v[42:45]
	v_mfma_f32_16x16x32_bf16 v[30:33], v[150:153], v[204:207], v[30:33]
	v_mfma_f32_16x16x32_bf16 v[26:29], v[164:167], v[204:207], v[26:29]
	v_mfma_f32_16x16x32_bf16 v[14:17], v[150:153], v[212:215], v[14:17]
	v_mfma_f32_16x16x32_bf16 v[10:13], v[164:167], v[212:215], v[10:13]
	s_setprio 0
	s_setprio 1
	v_mfma_f32_16x16x32_bf16 v[54:57], v[168:171], v[184:187], v[54:57]
	v_mfma_f32_16x16x32_bf16 v[50:53], v[176:179], v[184:187], v[50:53]
	v_mfma_f32_16x16x32_bf16 v[38:41], v[168:171], v[192:195], v[38:41]
	v_mfma_f32_16x16x32_bf16 v[34:37], v[176:179], v[192:195], v[34:37]
	v_mfma_f32_16x16x32_bf16 v[22:25], v[168:171], v[200:203], v[22:25]
	v_mfma_f32_16x16x32_bf16 v[18:21], v[176:179], v[200:203], v[18:21]
	v_mfma_f32_16x16x32_bf16 v[6:9], v[168:171], v[208:211], v[6:9]
	v_mfma_f32_16x16x32_bf16 v[2:5], v[176:179], v[208:211], v[2:5]
	v_mfma_f32_16x16x32_bf16 v[54:57], v[172:175], v[188:191], v[54:57]
	v_mfma_f32_16x16x32_bf16 v[50:53], v[180:183], v[188:191], v[50:53]
	v_mfma_f32_16x16x32_bf16 v[38:41], v[172:175], v[196:199], v[38:41]
	v_mfma_f32_16x16x32_bf16 v[34:37], v[180:183], v[196:199], v[34:37]
	v_mfma_f32_16x16x32_bf16 v[22:25], v[172:175], v[204:207], v[22:25]
	v_mfma_f32_16x16x32_bf16 v[18:21], v[180:183], v[204:207], v[18:21]
	v_mfma_f32_16x16x32_bf16 v[6:9], v[172:175], v[212:215], v[6:9]
	v_mfma_f32_16x16x32_bf16 v[2:5], v[180:183], v[212:215], v[2:5]
	s_setprio 0
	s_barrier
; #define PG8_STAGE(bufoff, gbase, voff) do { _Pragma("unroll") for (int _i = 0; _i < 2; ++_i) \
;         __builtin_amdgcn_global_load_lds((const unsigned*)((const char*)(gbase) + (voff)[_i]), (PG8_LAS unsigned*)(lds + (bufoff) + ldsw + _i * 8192), 16, 0, 0); } while (0)
; #define PG8_LDA(dst, b, h) do { _Pragma("unroll") for (int m = 0; m < 4; ++m) _Pragma("unroll") for (int k = 0; k < 2; ++k) dst[m][k] = *(const PG8_LAS bf16x8*)(lds + PG8_SA(b, h) + aoff + m * 2048 + k * 1024); } while (0)
; #define PG8_LDB(dst, b, h) do { _Pragma("unroll") for (int n = 0; n < 2; ++n) _Pragma("unroll") for (int k = 0; k < 2; ++k) dst[n][k] = *(const PG8_LAS bf16x8*)(lds + PG8_SB(b, h) + boff + n * 2048 + k * 1024); } while (0)
; #define PG8_MMA(ai, bj, At, Bt) do { __builtin_amdgcn_s_setprio(1); _Pragma("unroll") for (int m = 0; m < 4; ++m) _Pragma("unroll") for (int n = 0; n < 2; ++n) _Pragma("unroll") for (int k = 0; k < 2; ++k) \
;         acc[ai][bj][m][n] = __builtin_amdgcn_mfma_f32_16x16x32_bf16(Bt[n][k], At[m][k], acc[ai][bj][m][n], 0, 0, 0); __builtin_amdgcn_s_setprio(0); } while (0)
; #define PG8_WAIT_V(n) asm volatile("s_waitcnt vmcnt(" #n ")" ::: "memory")
; #define PG8_WAIT_L(n) asm volatile("s_waitcnt lgkmcnt(" #n ")" ::: "memory")
; #define PG8_BAR __builtin_amdgcn_s_barrier()
; #define PG8_SCHED __builtin_amdgcn_sched_barrier(0)
; template <class Epi, class Sched, bool ALIGN_EPI = false, bool SP2 = false, bool KSEG = false>
; __device__ __forceinline__ void gemm_phase(PG8_LAS unsigned char* lds, const Gemm g, const Sched& S, const Epi& E) {
;     ...
;             PG8_LDB(B0, 1, 0); PG8_LDB(B1, 1, 1); PG8_SCHED; PG8_LDA(At, 1, 0); PG8_STAGE(PG8_SA(0, 1), a2 + hstep, voffA);
;             PG8_WAIT_V(8); PG8_WAIT_L(0); PG8_BAR; PG8_MMA(0, 0, At, B0); PG8_MMA(0, 1, At, B1); PG8_BAR; PG8_SCHED;
	s_add_i32 s33, 0, 0x18000
	s_add_i32 s81, 0, 0x1c000
	ds_read_b128 v[146:149], v250
	ds_read_b128 v[150:153], v250 offset:1024
	ds_read_b128 v[160:163], v250 offset:2048
	ds_read_b128 v[164:167], v250 offset:3072
	ds_read_b128 v[168:171], v251
	ds_read_b128 v[172:175], v251 offset:1024
	ds_read_b128 v[176:179], v251 offset:2048
	ds_read_b128 v[180:183], v251 offset:3072
	s_mov_b32 m0, s27
	v_lshl_add_u64 v[224:225], s[42:43], 0, v[136:137]
	global_load_lds_dwordx4 v[224:225], off
	s_mov_b32 m0, s47
	v_lshl_add_u64 v[224:225], s[42:43], 0, v[132:133]
	global_load_lds_dwordx4 v[224:225], off
	s_add_u32 s42, s42, 0x80000
	s_addc_u32 s43, s43, 0
	s_mov_b32 m0, s48
	v_lshl_add_u64 v[224:225], s[42:43], 0, v[136:137]
	ds_read_b128 v[184:187], v158 offset:32768
	ds_read_b128 v[188:191], v158 offset:33792
	ds_read_b128 v[192:195], v158 offset:34816
	ds_read_b128 v[196:199], v158 offset:35840
	ds_read_b128 v[200:203], v158 offset:36864
	ds_read_b128 v[204:207], v158 offset:37888
	ds_read_b128 v[208:211], v158 offset:38912
	ds_read_b128 v[212:215], v158 offset:39936
	global_load_lds_dwordx4 v[224:225], off
	s_mov_b32 m0, s49
	v_lshl_add_u64 v[224:225], s[42:43], 0, v[132:133]
	global_load_lds_dwordx4 v[224:225], off
	s_waitcnt vmcnt(8) lgkmcnt(0)
	s_barrier
	s_setprio 1
	v_mfma_f32_16x16x32_bf16 v[126:129], v[146:149], v[184:187], v[126:129]
	v_mfma_f32_16x16x32_bf16 v[122:125], v[160:163], v[184:187], v[122:125]
	v_mfma_f32_16x16x32_bf16 v[110:113], v[146:149], v[192:195], v[110:113]
	v_mfma_f32_16x16x32_bf16 v[106:109], v[160:163], v[192:195], v[106:109]
	v_mfma_f32_16x16x32_bf16 v[94:97], v[146:149], v[200:203], v[94:97]
	v_mfma_f32_16x16x32_bf16 v[90:93], v[160:163], v[200:203], v[90:93]
	v_mfma_f32_16x16x32_bf16 v[78:81], v[146:149], v[208:211], v[78:81]
	v_mfma_f32_16x16x32_bf16 v[74:77], v[160:163], v[208:211], v[74:77]
	v_mfma_f32_16x16x32_bf16 v[126:129], v[150:153], v[188:191], v[126:129]
	v_mfma_f32_16x16x32_bf16 v[122:125], v[164:167], v[188:191], v[122:125]
	v_mfma_f32_16x16x32_bf16 v[110:113], v[150:153], v[196:199], v[110:113]
	v_mfma_f32_16x16x32_bf16 v[106:109], v[164:167], v[196:199], v[106:109]
	v_mfma_f32_16x16x32_bf16 v[94:97], v[150:153], v[204:207], v[94:97]
	v_mfma_f32_16x16x32_bf16 v[90:93], v[164:167], v[204:207], v[90:93]
	v_mfma_f32_16x16x32_bf16 v[78:81], v[150:153], v[212:215], v[78:81]
	v_mfma_f32_16x16x32_bf16 v[74:77], v[164:167], v[212:215], v[74:77]
	s_setprio 0
	s_setprio 1
	v_mfma_f32_16x16x32_bf16 v[118:121], v[168:171], v[184:187], v[118:121]
	v_mfma_f32_16x16x32_bf16 v[114:117], v[176:179], v[184:187], v[114:117]
	v_mfma_f32_16x16x32_bf16 v[102:105], v[168:171], v[192:195], v[102:105]
	v_mfma_f32_16x16x32_bf16 v[98:101], v[176:179], v[192:195], v[98:101]
	v_mfma_f32_16x16x32_bf16 v[86:89], v[168:171], v[200:203], v[86:89]
	v_mfma_f32_16x16x32_bf16 v[82:85], v[176:179], v[200:203], v[82:85]
	v_mfma_f32_16x16x32_bf16 v[70:73], v[168:171], v[208:211], v[70:73]
	v_mfma_f32_16x16x32_bf16 v[66:69], v[176:179], v[208:211], v[66:69]
	v_mfma_f32_16x16x32_bf16 v[118:121], v[172:175], v[188:191], v[118:121]
	v_mfma_f32_16x16x32_bf16 v[114:117], v[180:183], v[188:191], v[114:117]
	v_mfma_f32_16x16x32_bf16 v[102:105], v[172:175], v[196:199], v[102:105]
	v_mfma_f32_16x16x32_bf16 v[98:101], v[180:183], v[196:199], v[98:101]
	v_mfma_f32_16x16x32_bf16 v[86:89], v[172:175], v[204:207], v[86:89]
	v_mfma_f32_16x16x32_bf16 v[82:85], v[180:183], v[204:207], v[82:85]
	v_mfma_f32_16x16x32_bf16 v[70:73], v[172:175], v[212:215], v[70:73]
	v_mfma_f32_16x16x32_bf16 v[66:69], v[180:183], v[212:215], v[66:69]
	s_setprio 0
	s_barrier
; #define PG8_STAGE(bufoff, gbase, voff) do { _Pragma("unroll") for (int _i = 0; _i < 2; ++_i) \
;         __builtin_amdgcn_global_load_lds((const unsigned*)((const char*)(gbase) + (voff)[_i]), (PG8_LAS unsigned*)(lds + (bufoff) + ldsw + _i * 8192), 16, 0, 0); } while (0)
; #define PG8_LDA(dst, b, h) do { _Pragma("unroll") for (int m = 0; m < 4; ++m) _Pragma("unroll") for (int k = 0; k < 2; ++k) dst[m][k] = *(const PG8_LAS bf16x8*)(lds + PG8_SA(b, h) + aoff + m * 2048 + k * 1024); } while (0)
; #define PG8_MMA(ai, bj, At, Bt) do { __builtin_amdgcn_s_setprio(1); _Pragma("unroll") for (int m = 0; m < 4; ++m) _Pragma("unroll") for (int n = 0; n < 2; ++n) _Pragma("unroll") for (int k = 0; k < 2; ++k) \
;         acc[ai][bj][m][n] = __builtin_amdgcn_mfma_f32_16x16x32_bf16(Bt[n][k], At[m][k], acc[ai][bj][m][n], 0, 0, 0); __builtin_amdgcn_s_setprio(0); } while (0)
; #define PG8_WAIT_V(n) asm volatile("s_waitcnt vmcnt(" #n ")" ::: "memory")
; #define PG8_WAIT_L(n) asm volatile("s_waitcnt lgkmcnt(" #n ")" ::: "memory")
; #define PG8_BAR __builtin_amdgcn_s_barrier()
; #define PG8_SCHED __builtin_amdgcn_sched_barrier(0)
; template <class Epi, class Sched, bool ALIGN_EPI = false, bool SP2 = false, bool KSEG = false>
; __device__ __forceinline__ void gemm_phase(PG8_LAS unsigned char* lds, const Gemm g, const Sched& S, const Epi& E) {
;     ...
;         for (int t = 0; t < nt; t += 2) {
;             const bool last = (t == nt - 2);
;             const char* a1 = cA + (size_t)(t + 1) * kstep;
;             const char* a2 = last ? nA : cA + (size_t)(t + 2) * kstep; const char* b2 = last ? nB : cB + (size_t)(t + 2) * kstep;
;             const char* a3 = a2 + kstep; const char* b3 = b2 + kstep;
;     ...
;             PG8_LDA(At, 1, 1); PG8_STAGE(PG8_SB(1, 0), b3, voffB); PG8_STAGE(PG8_SB(1, 1), b3 + hstep, voffB); PG8_STAGE(PG8_SA(1, 0), a3, voffA);
;             PG8_WAIT_V(8); PG8_WAIT_L(0); PG8_BAR; PG8_MMA(1, 0, At, B0); PG8_MMA(1, 1, At, B1); PG8_BAR; PG8_SCHED;
	s_add_i32 s33, s33, s44
	v_lshl_add_u64 v[216:217], v[216:217], 0, s[12:13]
	s_mov_b32 m0, s33
	ds_read_b128 v[184:187], v158 offset:49152
	ds_read_b128 v[188:191], v158 offset:50176
	ds_read_b128 v[192:195], v158 offset:51200
	ds_read_b128 v[196:199], v158 offset:52224
	ds_read_b128 v[200:203], v158 offset:53248
	ds_read_b128 v[204:207], v158 offset:54272
	ds_read_b128 v[208:211], v158 offset:55296
	ds_read_b128 v[212:215], v158 offset:56320
	global_load_lds_dwordx4 v[216:217], off
	s_add_i32 m0, s33, 0x2000
	s_add_u32 s30, s30, 0x80080
	v_lshl_add_u64 v[216:217], v[218:219], 0, s[12:13]
	s_addc_u32 s31, s31, 0
	s_add_i32 s33, s81, s44
	global_load_lds_dwordx4 v[216:217], off
	s_mov_b32 m0, s33
	v_lshl_add_u64 v[216:217], s[30:31], 0, v[134:135]
	global_load_lds_dwordx4 v[216:217], off
	s_add_i32 m0, s33, 0x2000
	v_lshl_add_u64 v[216:217], s[30:31], 0, v[130:131]
	global_load_lds_dwordx4 v[216:217], off
	s_waitcnt vmcnt(6) lgkmcnt(0)
	s_barrier
	s_setprio 1
	v_mfma_f32_16x16x32_bf16 v[62:65], v[146:149], v[184:187], v[62:65]
	v_mfma_f32_16x16x32_bf16 v[58:61], v[160:163], v[184:187], v[58:61]
	v_mfma_f32_16x16x32_bf16 v[46:49], v[146:149], v[192:195], v[46:49]
	v_mfma_f32_16x16x32_bf16 v[42:45], v[160:163], v[192:195], v[42:45]
	v_mfma_f32_16x16x32_bf16 v[30:33], v[146:149], v[200:203], v[30:33]
	v_mfma_f32_16x16x32_bf16 v[26:29], v[160:163], v[200:203], v[26:29]
	v_mfma_f32_16x16x32_bf16 v[14:17], v[146:149], v[208:211], v[14:17]
	v_mfma_f32_16x16x32_bf16 v[10:13], v[160:163], v[208:211], v[10:13]
	v_mfma_f32_16x16x32_bf16 v[62:65], v[150:153], v[188:191], v[62:65]
	v_mfma_f32_16x16x32_bf16 v[58:61], v[164:167], v[188:191], v[58:61]
	v_mfma_f32_16x16x32_bf16 v[46:49], v[150:153], v[196:199], v[46:49]
	v_mfma_f32_16x16x32_bf16 v[42:45], v[164:167], v[196:199], v[42:45]
	v_mfma_f32_16x16x32_bf16 v[30:33], v[150:153], v[204:207], v[30:33]
	v_mfma_f32_16x16x32_bf16 v[26:29], v[164:167], v[204:207], v[26:29]
	v_mfma_f32_16x16x32_bf16 v[14:17], v[150:153], v[212:215], v[14:17]
	v_mfma_f32_16x16x32_bf16 v[10:13], v[164:167], v[212:215], v[10:13]
	s_setprio 0
	s_setprio 1
	v_mfma_f32_16x16x32_bf16 v[54:57], v[168:171], v[184:187], v[54:57]
	s_add_i32 s80, s80, 2
	v_mfma_f32_16x16x32_bf16 v[50:53], v[176:179], v[184:187], v[50:53]
	s_add_u32 s28, s28, 0x100
	v_mfma_f32_16x16x32_bf16 v[38:41], v[168:171], v[192:195], v[38:41]
	s_addc_u32 s29, s29, 0
	v_mfma_f32_16x16x32_bf16 v[34:37], v[176:179], v[192:195], v[34:37]
	s_add_u32 s66, s66, 0x100
	v_mfma_f32_16x16x32_bf16 v[22:25], v[168:171], v[200:203], v[22:25]
	s_addc_u32 s67, s67, 0
	v_mfma_f32_16x16x32_bf16 v[18:21], v[176:179], v[200:203], v[18:21]
	s_add_u32 s30, s28, 0xfff80080
	v_mfma_f32_16x16x32_bf16 v[6:9], v[168:171], v[208:211], v[6:9]
	s_addc_u32 s31, s29, -1
	v_mfma_f32_16x16x32_bf16 v[2:5], v[176:179], v[208:211], v[2:5]
	s_cmp_eq_u32 s80, 28
	v_mfma_f32_16x16x32_bf16 v[54:57], v[172:175], v[188:191], v[54:57]
	s_cselect_b32 s43, s21, s31
	v_mfma_f32_16x16x32_bf16 v[50:53], v[180:183], v[188:191], v[50:53]
	s_cselect_b32 s42, s64, s30
	v_mfma_f32_16x16x32_bf16 v[38:41], v[172:175], v[196:199], v[38:41]
	s_cselect_b32 s31, s19, s67
	v_mfma_f32_16x16x32_bf16 v[34:37], v[180:183], v[196:199], v[34:37]
	s_cselect_b32 s30, s65, s66
	v_mfma_f32_16x16x32_bf16 v[22:25], v[172:175], v[204:207], v[22:25]
	s_add_u32 s98, s28, 0xfff80000
	v_mfma_f32_16x16x32_bf16 v[18:21], v[180:183], v[204:207], v[18:21]
	s_addc_u32 s99, s29, -1
	v_mfma_f32_16x16x32_bf16 v[6:9], v[172:175], v[212:215], v[6:9]
	s_cmp_gt_u32 s80, 29
	v_mfma_f32_16x16x32_bf16 v[2:5], v[180:183], v[212:215], v[2:5]
	s_setprio 0
	s_barrier
	s_cbranch_scc0 .LBB0_120
	s_and_b64 vcc, exec, s[16:17]
	s_cbranch_vccz .LBB0_123
	s_barrier

; template <class Epi, class Sched, bool ALIGN_EPI = false, bool SP2 = false, bool KSEG = false>
; __device__ __forceinline__ void gemm_phase(PG8_LAS unsigned char* lds, const Gemm g, const Sched& S, const Epi& E) {
;     ...
;         const bool has_next = S.next(ui + 1, nxt);
;         const char* nA = has_next ? (const char*)g.A + (size_t)nxt.pm * tstep : cA; const char* nB = has_next ? (const char*)g.Bt + (size_t)nxt.pn * tstep : cB;
;         for (int t = 0; t < nt; t += 2) {
;             const bool last = (t == nt - 2);
;             const char* a1 = cA + (size_t)(t + 1) * kstep;
;             const char* a2 = last ? nA : cA + (size_t)(t + 2) * kstep; const char* b2 = last ? nB : cB + (size_t)(t + 2) * kstep;
;             const char* a3 = a2 + kstep; const char* b3 = b2 + kstep;
;     ...
; #pragma unroll
;         for (int a = 0; a < 2; ++a)
; #pragma unroll
;             for (int b = 0; b < 2; ++b)
; #pragma unroll
;                 for (int m = 0; m < 4; ++m)
; #pragma unroll
;                     for (int n = 0; n < 2; ++n) acc[a][b][m][n] = (f32x4){0.f, 0.f, 0.f, 0.f};
;         cur = nxt; cA = nA; cB = nB; ++ui;
.LBB0_496:
	s_ashr_i32 s25, s24, 31
	s_lshl_b64 s[26:27], s[24:25], 20
	s_add_u32 s26, s16, s26
	s_addc_u32 s27, s17, s27
	s_and_b64 s[28:29], s[4:5], exec
	s_cselect_b32 s25, s27, s37
	s_cselect_b32 s58, s26, s36
	s_ashr_i32 s23, s22, 31
	s_lshl_b64 s[28:29], s[22:23], 20
	s_add_u32 s28, s76, s28
	s_addc_u32 s29, s77, s29
	s_and_b64 s[40:41], s[4:5], exec
	s_cselect_b32 s23, s29, s39
	s_cselect_b32 s59, s28, s38
	s_add_u32 s36, s36, 0x80080
	s_addc_u32 s37, s37, 0
	s_add_u32 s60, s38, 0x100
	v_mov_b32_e32 v2, 0
	s_addc_u32 s61, s39, 0
	s_mov_b32 s62, -2
	v_mov_b32_e32 v3, v2
	v_mov_b32_e32 v4, v2
	v_mov_b32_e32 v5, v2
	v_mov_b32_e32 v6, v2
	v_mov_b32_e32 v7, v2
	v_mov_b32_e32 v8, v2
	v_mov_b32_e32 v9, v2
	v_mov_b32_e32 v18, v2
	v_mov_b32_e32 v19, v2
	v_mov_b32_e32 v20, v2
	v_mov_b32_e32 v21, v2
	v_mov_b32_e32 v22, v2
	v_mov_b32_e32 v23, v2
	v_mov_b32_e32 v24, v2
	v_mov_b32_e32 v25, v2
	v_mov_b32_e32 v34, v2
	v_mov_b32_e32 v35, v2
	v_mov_b32_e32 v36, v2
	v_mov_b32_e32 v37, v2
	v_mov_b32_e32 v38, v2
	s_waitcnt lgkmcnt(0)
	v_mov_b32_e32 v39, v2
	v_mov_b32_e32 v40, v2
	v_mov_b32_e32 v41, v2
	v_mov_b32_e32 v50, v2
	v_mov_b32_e32 v51, v2
	v_mov_b32_e32 v52, v2
	v_mov_b32_e32 v53, v2
	v_mov_b32_e32 v54, v2
	v_mov_b32_e32 v55, v2
	v_mov_b32_e32 v56, v2
	v_mov_b32_e32 v57, v2
	v_mov_b32_e32 v10, v2
	v_mov_b32_e32 v11, v2
	v_mov_b32_e32 v12, v2
	v_mov_b32_e32 v13, v2
	v_mov_b32_e32 v14, v2
	v_mov_b32_e32 v15, v2
	v_mov_b32_e32 v16, v2
	v_mov_b32_e32 v17, v2
	v_mov_b32_e32 v26, v2
	v_mov_b32_e32 v27, v2
	v_mov_b32_e32 v28, v2
	v_mov_b32_e32 v29, v2
	v_mov_b32_e32 v30, v2
	v_mov_b32_e32 v31, v2
	v_mov_b32_e32 v32, v2
	v_mov_b32_e32 v33, v2
	v_mov_b32_e32 v42, v2
	v_mov_b32_e32 v43, v2
	v_mov_b32_e32 v44, v2
	v_mov_b32_e32 v45, v2
	v_mov_b32_e32 v46, v2
	v_mov_b32_e32 v47, v2
	v_mov_b32_e32 v48, v2
	v_mov_b32_e32 v49, v2
	v_mov_b32_e32 v58, v2
	v_mov_b32_e32 v59, v2
	v_mov_b32_e32 v60, v2
	v_mov_b32_e32 v61, v2
	v_mov_b32_e32 v62, v2
	v_mov_b32_e32 v63, v2
	v_mov_b32_e32 v64, v2
	v_mov_b32_e32 v65, v2
	v_mov_b32_e32 v66, v2
	v_mov_b32_e32 v67, v2
	v_mov_b32_e32 v68, v2
	v_mov_b32_e32 v69, v2
	v_mov_b32_e32 v70, v2
	v_mov_b32_e32 v71, v2
	v_mov_b32_e32 v72, v2
	v_mov_b32_e32 v73, v2
	v_mov_b32_e32 v82, v2
	v_mov_b32_e32 v83, v2
	v_mov_b32_e32 v84, v2
	v_mov_b32_e32 v85, v2
	v_mov_b32_e32 v86, v2
	v_mov_b32_e32 v87, v2
	v_mov_b32_e32 v88, v2
	v_mov_b32_e32 v89, v2
	v_mov_b32_e32 v98, v2
	v_mov_b32_e32 v99, v2
	v_mov_b32_e32 v100, v2
	v_mov_b32_e32 v101, v2
	v_mov_b32_e32 v102, v2
	v_mov_b32_e32 v103, v2
	v_mov_b32_e32 v104, v2
	v_mov_b32_e32 v105, v2
	v_mov_b32_e32 v114, v2
	v_mov_b32_e32 v115, v2
	v_mov_b32_e32 v116, v2
	v_mov_b32_e32 v117, v2
	v_mov_b32_e32 v118, v2
	v_mov_b32_e32 v119, v2
	v_mov_b32_e32 v120, v2
	v_mov_b32_e32 v121, v2
	v_mov_b32_e32 v74, v2
	v_mov_b32_e32 v75, v2
	v_mov_b32_e32 v76, v2
	v_mov_b32_e32 v77, v2
	v_mov_b32_e32 v78, v2
	v_mov_b32_e32 v79, v2
	v_mov_b32_e32 v80, v2
	v_mov_b32_e32 v81, v2
	v_mov_b32_e32 v90, v2
	v_mov_b32_e32 v91, v2
	v_mov_b32_e32 v92, v2
	v_mov_b32_e32 v93, v2
	v_mov_b32_e32 v94, v2
	v_mov_b32_e32 v95, v2
	v_mov_b32_e32 v96, v2
	v_mov_b32_e32 v97, v2
	v_mov_b32_e32 v106, v2
	v_mov_b32_e32 v107, v2
	v_mov_b32_e32 v108, v2
	v_mov_b32_e32 v109, v2
	v_mov_b32_e32 v110, v2
	v_mov_b32_e32 v111, v2
	v_mov_b32_e32 v112, v2
	v_mov_b32_e32 v113, v2
	v_mov_b32_e32 v122, v2
	v_mov_b32_e32 v123, v2
	v_mov_b32_e32 v124, v2
	v_mov_b32_e32 v125, v2
	v_mov_b32_e32 v126, v2
	v_mov_b32_e32 v127, v2
	v_mov_b32_e32 v128, v2
	v_mov_b32_e32 v129, v2
	s_add_u32 s33, s36, 0xfff80080
	s_addc_u32 s38, s37, -1
	s_cmp_eq_u32 s62, 28
	s_cselect_b32 s41, s25, s38
	s_cselect_b32 s40, s58, s33
	s_cselect_b32 s39, s23, s61
	s_cselect_b32 s38, s59, s60
	s_add_u32 s98, s36, 0xfff80000
	s_addc_u32 s99, s37, -1
	v_add_u32_e32 v250, 0x18000, v166
	v_add_u32_e32 v251, 0x1c000, v166
.LBB0_497:
	ds_read_b128 v[148:151], v168
	ds_read_b128 v[172:175], v168 offset:1024
	ds_read_b128 v[176:179], v168 offset:2048
	ds_read_b128 v[180:183], v168 offset:3072
	ds_read_b128 v[184:187], v169
	ds_read_b128 v[188:191], v169 offset:1024
	ds_read_b128 v[192:195], v169 offset:2048
	ds_read_b128 v[196:199], v169 offset:3072
	s_mov_b32 m0, s52
	v_lshl_add_u64 v[232:233], s[98:99], 0, v[132:133]
	global_load_lds_dwordx4 v[232:233], off
	s_mov_b32 m0, s53
	v_lshl_add_u64 v[232:233], s[98:99], 0, v[136:137]
	global_load_lds_dwordx4 v[232:233], off
	v_lshl_add_u64 v[232:233], s[36:37], 0, v[140:141]
	s_add_i32 m0, s31, 0xc000
	ds_read_b128 v[200:203], v170
	ds_read_b128 v[204:207], v170 offset:1024
	ds_read_b128 v[208:211], v170 offset:2048
	ds_read_b128 v[212:215], v170 offset:3072
	ds_read_b128 v[216:219], v170 offset:4096
	ds_read_b128 v[220:223], v170 offset:5120
	ds_read_b128 v[224:227], v170 offset:6144
	ds_read_b128 v[228:231], v170 offset:7168
	global_load_lds_dwordx4 v[232:233], off
	s_add_i32 m0, s31, 0xe000
	v_lshl_add_u64 v[232:233], s[36:37], 0, v[142:143]
	global_load_lds_dwordx4 v[232:233], off
	s_waitcnt vmcnt(8) lgkmcnt(0)
	s_barrier
; #define PG8_STAGE(bufoff, gbase, voff) do { _Pragma("unroll") for (int _i = 0; _i < 2; ++_i) \
;         __builtin_amdgcn_global_load_lds((const unsigned*)((const char*)(gbase) + (voff)[_i]), (PG8_LAS unsigned*)(lds + (bufoff) + ldsw + _i * 8192), 16, 0, 0); } while (0)
; #define PG8_LDA(dst, b, h) do { _Pragma("unroll") for (int m = 0; m < 4; ++m) _Pragma("unroll") for (int k = 0; k < 2; ++k) dst[m][k] = *(const PG8_LAS bf16x8*)(lds + PG8_SA(b, h) + aoff + m * 2048 + k * 1024); } while (0)
; #define PG8_LDB(dst, b, h) do { _Pragma("unroll") for (int n = 0; n < 2; ++n) _Pragma("unroll") for (int k = 0; k < 2; ++k) dst[n][k] = *(const PG8_LAS bf16x8*)(lds + PG8_SB(b, h) + boff + n * 2048 + k * 1024); } while (0)
; #define PG8_MMA(ai, bj, At, Bt) do { __builtin_amdgcn_s_setprio(1); _Pragma("unroll") for (int m = 0; m < 4; ++m) _Pragma("unroll") for (int n = 0; n < 2; ++n) _Pragma("unroll") for (int k = 0; k < 2; ++k) \
;         acc[ai][bj][m][n] = __builtin_amdgcn_mfma_f32_16x16x32_bf16(Bt[n][k], At[m][k], acc[ai][bj][m][n], 0, 0, 0); __builtin_amdgcn_s_setprio(0); } while (0)
; #define PG8_WAIT_V(n) asm volatile("s_waitcnt vmcnt(" #n ")" ::: "memory")
; #define PG8_WAIT_L(n) asm volatile("s_waitcnt lgkmcnt(" #n ")" ::: "memory")
; #define PG8_BAR __builtin_amdgcn_s_barrier()
; #define PG8_SCHED __builtin_amdgcn_sched_barrier(0)
; template <class Epi, class Sched, bool ALIGN_EPI = false, bool SP2 = false, bool KSEG = false>
; __device__ __forceinline__ void gemm_phase(PG8_LAS unsigned char* lds, const Gemm g, const Sched& S, const Epi& E) {
;     ...
;             PG8_LDB(B0, 0, 0); PG8_LDB(B1, 0, 1); PG8_SCHED; PG8_LDA(At, 0, 0); PG8_STAGE(PG8_SA(1, 1), a1 + hstep, voffA);
;             PG8_WAIT_V(8); PG8_WAIT_L(0); PG8_BAR; PG8_MMA(0, 0, At, B0); PG8_MMA(0, 1, At, B1); PG8_BAR; PG8_SCHED;
;             PG8_LDA(At, 0, 1); PG8_STAGE(PG8_SB(0, 0), b2, voffB); PG8_STAGE(PG8_SB(0, 1), b2 + hstep, voffB); PG8_STAGE(PG8_SA(0, 0), a2, voffA);
;             PG8_WAIT_V(8); PG8_WAIT_L(0); PG8_BAR; PG8_MMA(1, 0, At, B0); PG8_MMA(1, 1, At, B1); PG8_BAR; PG8_SCHED;
	s_setprio 1
	v_mfma_f32_16x16x32_bf16 v[126:129], v[148:151], v[200:203], v[126:129]
	v_mfma_f32_16x16x32_bf16 v[122:125], v[176:179], v[200:203], v[122:125]
	v_mfma_f32_16x16x32_bf16 v[110:113], v[148:151], v[208:211], v[110:113]
	v_mfma_f32_16x16x32_bf16 v[106:109], v[176:179], v[208:211], v[106:109]
	v_mfma_f32_16x16x32_bf16 v[94:97], v[148:151], v[216:219], v[94:97]
	v_mfma_f32_16x16x32_bf16 v[90:93], v[176:179], v[216:219], v[90:93]
	v_mfma_f32_16x16x32_bf16 v[78:81], v[148:151], v[224:227], v[78:81]
	v_mfma_f32_16x16x32_bf16 v[74:77], v[176:179], v[224:227], v[74:77]
	v_mfma_f32_16x16x32_bf16 v[126:129], v[172:175], v[204:207], v[126:129]
	v_mfma_f32_16x16x32_bf16 v[122:125], v[180:183], v[204:207], v[122:125]
	v_mfma_f32_16x16x32_bf16 v[110:113], v[172:175], v[212:215], v[110:113]
	v_mfma_f32_16x16x32_bf16 v[106:109], v[180:183], v[212:215], v[106:109]
	v_mfma_f32_16x16x32_bf16 v[94:97], v[172:175], v[220:223], v[94:97]
	v_mfma_f32_16x16x32_bf16 v[90:93], v[180:183], v[220:223], v[90:93]
	v_mfma_f32_16x16x32_bf16 v[78:81], v[172:175], v[228:231], v[78:81]
	v_mfma_f32_16x16x32_bf16 v[74:77], v[180:183], v[228:231], v[74:77]
	s_setprio 0
	s_setprio 1
	v_mfma_f32_16x16x32_bf16 v[118:121], v[184:187], v[200:203], v[118:121]
	v_mfma_f32_16x16x32_bf16 v[114:117], v[192:195], v[200:203], v[114:117]
	v_mfma_f32_16x16x32_bf16 v[102:105], v[184:187], v[208:211], v[102:105]
	v_mfma_f32_16x16x32_bf16 v[98:101], v[192:195], v[208:211], v[98:101]
	v_mfma_f32_16x16x32_bf16 v[86:89], v[184:187], v[216:219], v[86:89]
	v_mfma_f32_16x16x32_bf16 v[82:85], v[192:195], v[216:219], v[82:85]
	v_mfma_f32_16x16x32_bf16 v[70:73], v[184:187], v[224:227], v[70:73]
	v_mfma_f32_16x16x32_bf16 v[66:69], v[192:195], v[224:227], v[66:69]
	v_mfma_f32_16x16x32_bf16 v[118:121], v[188:191], v[204:207], v[118:121]
	v_mfma_f32_16x16x32_bf16 v[114:117], v[196:199], v[204:207], v[114:117]
	v_mfma_f32_16x16x32_bf16 v[102:105], v[188:191], v[212:215], v[102:105]
	v_mfma_f32_16x16x32_bf16 v[98:101], v[196:199], v[212:215], v[98:101]
	v_mfma_f32_16x16x32_bf16 v[86:89], v[188:191], v[220:223], v[86:89]
	v_mfma_f32_16x16x32_bf16 v[82:85], v[196:199], v[220:223], v[82:85]
	v_mfma_f32_16x16x32_bf16 v[70:73], v[188:191], v[228:231], v[70:73]
	v_mfma_f32_16x16x32_bf16 v[66:69], v[196:199], v[228:231], v[66:69]
	s_setprio 0
	s_barrier
	s_add_i32 s33, s54, s43
	v_lshl_add_u64 v[232:233], s[38:39], 0, v[134:135]
	s_mov_b32 m0, s33
	ds_read_b128 v[200:203], v170 offset:16384
	ds_read_b128 v[204:207], v170 offset:17408
	ds_read_b128 v[208:211], v170 offset:18432
	ds_read_b128 v[212:215], v170 offset:19456
	ds_read_b128 v[216:219], v170 offset:20480
	ds_read_b128 v[220:223], v170 offset:21504
	ds_read_b128 v[224:227], v170 offset:22528
	ds_read_b128 v[228:231], v170 offset:23552
	global_load_lds_dwordx4 v[232:233], off
	s_add_i32 m0, s33, 0x2000
	s_add_u32 s64, s38, 0x80000
	v_lshl_add_u64 v[234:235], s[38:39], 0, v[138:139]
	s_addc_u32 s65, s39, 0
	s_add_i32 s33, s55, s43
	global_load_lds_dwordx4 v[234:235], off
	s_mov_b32 m0, s33
	v_lshl_add_u64 v[236:237], s[64:65], 0, v[134:135]
	global_load_lds_dwordx4 v[236:237], off
	s_add_i32 m0, s33, 0x2000
	v_lshl_add_u64 v[236:237], s[64:65], 0, v[138:139]
	global_load_lds_dwordx4 v[236:237], off
	s_waitcnt vmcnt(6) lgkmcnt(0)
	s_barrier
	s_setprio 1
	v_mfma_f32_16x16x32_bf16 v[62:65], v[148:151], v[200:203], v[62:65]
	v_mfma_f32_16x16x32_bf16 v[58:61], v[176:179], v[200:203], v[58:61]
	v_mfma_f32_16x16x32_bf16 v[46:49], v[148:151], v[208:211], v[46:49]
	v_mfma_f32_16x16x32_bf16 v[42:45], v[176:179], v[208:211], v[42:45]
	v_mfma_f32_16x16x32_bf16 v[30:33], v[148:151], v[216:219], v[30:33]
	v_mfma_f32_16x16x32_bf16 v[26:29], v[176:179], v[216:219], v[26:29]
	v_mfma_f32_16x16x32_bf16 v[14:17], v[148:151], v[224:227], v[14:17]
	v_mfma_f32_16x16x32_bf16 v[10:13], v[176:179], v[224:227], v[10:13]
	v_mfma_f32_16x16x32_bf16 v[62:65], v[172:175], v[204:207], v[62:65]
	v_mfma_f32_16x16x32_bf16 v[58:61], v[180:183], v[204:207], v[58:61]
	v_mfma_f32_16x16x32_bf16 v[46:49], v[172:175], v[212:215], v[46:49]
	v_mfma_f32_16x16x32_bf16 v[42:45], v[180:183], v[212:215], v[42:45]
	v_mfma_f32_16x16x32_bf16 v[30:33], v[172:175], v[220:223], v[30:33]
	v_mfma_f32_16x16x32_bf16 v[26:29], v[180:183], v[220:223], v[26:29]
	v_mfma_f32_16x16x32_bf16 v[14:17], v[172:175], v[228:231], v[14:17]
	v_mfma_f32_16x16x32_bf16 v[10:13], v[180:183], v[228:231], v[10:13]
	s_setprio 0
	s_setprio 1
	v_mfma_f32_16x16x32_bf16 v[54:57], v[184:187], v[200:203], v[54:57]
	v_mfma_f32_16x16x32_bf16 v[50:53], v[192:195], v[200:203], v[50:53]
	v_mfma_f32_16x16x32_bf16 v[38:41], v[184:187], v[208:211], v[38:41]
	v_mfma_f32_16x16x32_bf16 v[34:37], v[192:195], v[208:211], v[34:37]
	v_mfma_f32_16x16x32_bf16 v[22:25], v[184:187], v[216:219], v[22:25]
	v_mfma_f32_16x16x32_bf16 v[18:21], v[192:195], v[216:219], v[18:21]
	v_mfma_f32_16x16x32_bf16 v[6:9], v[184:187], v[224:227], v[6:9]
	v_mfma_f32_16x16x32_bf16 v[2:5], v[192:195], v[224:227], v[2:5]
	v_mfma_f32_16x16x32_bf16 v[54:57], v[188:191], v[204:207], v[54:57]
	v_mfma_f32_16x16x32_bf16 v[50:53], v[196:199], v[204:207], v[50:53]
	v_mfma_f32_16x16x32_bf16 v[38:41], v[188:191], v[212:215], v[38:41]
	v_mfma_f32_16x16x32_bf16 v[34:37], v[196:199], v[212:215], v[34:37]
	v_mfma_f32_16x16x32_bf16 v[22:25], v[188:191], v[220:223], v[22:25]
	v_mfma_f32_16x16x32_bf16 v[18:21], v[196:199], v[220:223], v[18:21]
	v_mfma_f32_16x16x32_bf16 v[6:9], v[188:191], v[228:231], v[6:9]
	v_mfma_f32_16x16x32_bf16 v[2:5], v[196:199], v[228:231], v[2:5]
	s_setprio 0
	s_barrier
; #define PG8_STAGE(bufoff, gbase, voff) do { _Pragma("unroll") for (int _i = 0; _i < 2; ++_i) \
;         __builtin_amdgcn_global_load_lds((const unsigned*)((const char*)(gbase) + (voff)[_i]), (PG8_LAS unsigned*)(lds + (bufoff) + ldsw + _i * 8192), 16, 0, 0); } while (0)
; #define PG8_LDA(dst, b, h) do { _Pragma("unroll") for (int m = 0; m < 4; ++m) _Pragma("unroll") for (int k = 0; k < 2; ++k) dst[m][k] = *(const PG8_LAS bf16x8*)(lds + PG8_SA(b, h) + aoff + m * 2048 + k * 1024); } while (0)
; #define PG8_LDB(dst, b, h) do { _Pragma("unroll") for (int n = 0; n < 2; ++n) _Pragma("unroll") for (int k = 0; k < 2; ++k) dst[n][k] = *(const PG8_LAS bf16x8*)(lds + PG8_SB(b, h) + boff + n * 2048 + k * 1024); } while (0)
; #define PG8_MMA(ai, bj, At, Bt) do { __builtin_amdgcn_s_setprio(1); _Pragma("unroll") for (int m = 0; m < 4; ++m) _Pragma("unroll") for (int n = 0; n < 2; ++n) _Pragma("unroll") for (int k = 0; k < 2; ++k) \
;         acc[ai][bj][m][n] = __builtin_amdgcn_mfma_f32_16x16x32_bf16(Bt[n][k], At[m][k], acc[ai][bj][m][n], 0, 0, 0); __builtin_amdgcn_s_setprio(0); } while (0)
; #define PG8_WAIT_V(n) asm volatile("s_waitcnt vmcnt(" #n ")" ::: "memory")
; #define PG8_WAIT_L(n) asm volatile("s_waitcnt lgkmcnt(" #n ")" ::: "memory")
; #define PG8_BAR __builtin_amdgcn_s_barrier()
; #define PG8_SCHED __builtin_amdgcn_sched_barrier(0)
; template <class Epi, class Sched, bool ALIGN_EPI = false, bool SP2 = false, bool KSEG = false>
; __device__ __forceinline__ void gemm_phase(PG8_LAS unsigned char* lds, const Gemm g, const Sched& S, const Epi& E) {
;     ...
;             PG8_LDB(B0, 1, 0); PG8_LDB(B1, 1, 1); PG8_SCHED; PG8_LDA(At, 1, 0); PG8_STAGE(PG8_SA(0, 1), a2 + hstep, voffA);
;             PG8_WAIT_V(8); PG8_WAIT_L(0); PG8_BAR; PG8_MMA(0, 0, At, B0); PG8_MMA(0, 1, At, B1); PG8_BAR; PG8_SCHED;
	s_add_i32 s33, 0, 0x18000
	s_add_i32 s63, 0, 0x1c000
	ds_read_b128 v[148:151], v250
	ds_read_b128 v[172:175], v250 offset:1024
	ds_read_b128 v[176:179], v250 offset:2048
	ds_read_b128 v[180:183], v250 offset:3072
	ds_read_b128 v[184:187], v251
	ds_read_b128 v[188:191], v251 offset:1024
	ds_read_b128 v[192:195], v251 offset:2048
	ds_read_b128 v[196:199], v251 offset:3072
	s_mov_b32 m0, s31
	v_lshl_add_u64 v[240:241], s[40:41], 0, v[132:133]
	global_load_lds_dwordx4 v[240:241], off
	s_mov_b32 m0, s45
	v_lshl_add_u64 v[240:241], s[40:41], 0, v[136:137]
	global_load_lds_dwordx4 v[240:241], off
	s_add_u32 s40, s40, 0x80000
	s_addc_u32 s41, s41, 0
	s_mov_b32 m0, s49
	v_lshl_add_u64 v[240:241], s[40:41], 0, v[132:133]
	ds_read_b128 v[200:203], v170 offset:32768
	ds_read_b128 v[204:207], v170 offset:33792
	ds_read_b128 v[208:211], v170 offset:34816
	ds_read_b128 v[212:215], v170 offset:35840
	ds_read_b128 v[216:219], v170 offset:36864
	ds_read_b128 v[220:223], v170 offset:37888
	ds_read_b128 v[224:227], v170 offset:38912
	ds_read_b128 v[228:231], v170 offset:39936
	global_load_lds_dwordx4 v[240:241], off
	s_mov_b32 m0, s50
	v_lshl_add_u64 v[240:241], s[40:41], 0, v[136:137]
	global_load_lds_dwordx4 v[240:241], off
	s_waitcnt vmcnt(8) lgkmcnt(0)
	s_barrier
	s_setprio 1
	v_mfma_f32_16x16x32_bf16 v[126:129], v[148:151], v[200:203], v[126:129]
	v_mfma_f32_16x16x32_bf16 v[122:125], v[176:179], v[200:203], v[122:125]
	v_mfma_f32_16x16x32_bf16 v[110:113], v[148:151], v[208:211], v[110:113]
	v_mfma_f32_16x16x32_bf16 v[106:109], v[176:179], v[208:211], v[106:109]
	v_mfma_f32_16x16x32_bf16 v[94:97], v[148:151], v[216:219], v[94:97]
	v_mfma_f32_16x16x32_bf16 v[90:93], v[176:179], v[216:219], v[90:93]
	v_mfma_f32_16x16x32_bf16 v[78:81], v[148:151], v[224:227], v[78:81]
	v_mfma_f32_16x16x32_bf16 v[74:77], v[176:179], v[224:227], v[74:77]
	v_mfma_f32_16x16x32_bf16 v[126:129], v[172:175], v[204:207], v[126:129]
	v_mfma_f32_16x16x32_bf16 v[122:125], v[180:183], v[204:207], v[122:125]
	v_mfma_f32_16x16x32_bf16 v[110:113], v[172:175], v[212:215], v[110:113]
	v_mfma_f32_16x16x32_bf16 v[106:109], v[180:183], v[212:215], v[106:109]
	v_mfma_f32_16x16x32_bf16 v[94:97], v[172:175], v[220:223], v[94:97]
	v_mfma_f32_16x16x32_bf16 v[90:93], v[180:183], v[220:223], v[90:93]
	v_mfma_f32_16x16x32_bf16 v[78:81], v[172:175], v[228:231], v[78:81]
	v_mfma_f32_16x16x32_bf16 v[74:77], v[180:183], v[228:231], v[74:77]
	s_setprio 0
	s_setprio 1
	v_mfma_f32_16x16x32_bf16 v[118:121], v[184:187], v[200:203], v[118:121]
	v_mfma_f32_16x16x32_bf16 v[114:117], v[192:195], v[200:203], v[114:117]
	v_mfma_f32_16x16x32_bf16 v[102:105], v[184:187], v[208:211], v[102:105]
	v_mfma_f32_16x16x32_bf16 v[98:101], v[192:195], v[208:211], v[98:101]
	v_mfma_f32_16x16x32_bf16 v[86:89], v[184:187], v[216:219], v[86:89]
	v_mfma_f32_16x16x32_bf16 v[82:85], v[192:195], v[216:219], v[82:85]
	v_mfma_f32_16x16x32_bf16 v[70:73], v[184:187], v[224:227], v[70:73]
	v_mfma_f32_16x16x32_bf16 v[66:69], v[192:195], v[224:227], v[66:69]
	v_mfma_f32_16x16x32_bf16 v[118:121], v[188:191], v[204:207], v[118:121]
	v_mfma_f32_16x16x32_bf16 v[114:117], v[196:199], v[204:207], v[114:117]
	v_mfma_f32_16x16x32_bf16 v[102:105], v[188:191], v[212:215], v[102:105]
	v_mfma_f32_16x16x32_bf16 v[98:101], v[196:199], v[212:215], v[98:101]
	v_mfma_f32_16x16x32_bf16 v[86:89], v[188:191], v[220:223], v[86:89]
	v_mfma_f32_16x16x32_bf16 v[82:85], v[196:199], v[220:223], v[82:85]
	v_mfma_f32_16x16x32_bf16 v[70:73], v[188:191], v[228:231], v[70:73]
	v_mfma_f32_16x16x32_bf16 v[66:69], v[196:199], v[228:231], v[66:69]
	s_setprio 0
	s_barrier
; #define PG8_STAGE(bufoff, gbase, voff) do { _Pragma("unroll") for (int _i = 0; _i < 2; ++_i) \
;         __builtin_amdgcn_global_load_lds((const unsigned*)((const char*)(gbase) + (voff)[_i]), (PG8_LAS unsigned*)(lds + (bufoff) + ldsw + _i * 8192), 16, 0, 0); } while (0)
; #define PG8_LDA(dst, b, h) do { _Pragma("unroll") for (int m = 0; m < 4; ++m) _Pragma("unroll") for (int k = 0; k < 2; ++k) dst[m][k] = *(const PG8_LAS bf16x8*)(lds + PG8_SA(b, h) + aoff + m * 2048 + k * 1024); } while (0)
; #define PG8_MMA(ai, bj, At, Bt) do { __builtin_amdgcn_s_setprio(1); _Pragma("unroll") for (int m = 0; m < 4; ++m) _Pragma("unroll") for (int n = 0; n < 2; ++n) _Pragma("unroll") for (int k = 0; k < 2; ++k) \
;         acc[ai][bj][m][n] = __builtin_amdgcn_mfma_f32_16x16x32_bf16(Bt[n][k], At[m][k], acc[ai][bj][m][n], 0, 0, 0); __builtin_amdgcn_s_setprio(0); } while (0)
; #define PG8_WAIT_V(n) asm volatile("s_waitcnt vmcnt(" #n ")" ::: "memory")
; #define PG8_WAIT_L(n) asm volatile("s_waitcnt lgkmcnt(" #n ")" ::: "memory")
; #define PG8_BAR __builtin_amdgcn_s_barrier()
; #define PG8_SCHED __builtin_amdgcn_sched_barrier(0)
; template <class Epi, class Sched, bool ALIGN_EPI = false, bool SP2 = false, bool KSEG = false>
; __device__ __forceinline__ void gemm_phase(PG8_LAS unsigned char* lds, const Gemm g, const Sched& S, const Epi& E) {
;     ...
;         for (int t = 0; t < nt; t += 2) {
;             const bool last = (t == nt - 2);
;             const char* a1 = cA + (size_t)(t + 1) * kstep;
;             const char* a2 = last ? nA : cA + (size_t)(t + 2) * kstep; const char* b2 = last ? nB : cB + (size_t)(t + 2) * kstep;
;             const char* a3 = a2 + kstep; const char* b3 = b2 + kstep;
;     ...
;             PG8_LDA(At, 1, 1); PG8_STAGE(PG8_SB(1, 0), b3, voffB); PG8_STAGE(PG8_SB(1, 1), b3 + hstep, voffB); PG8_STAGE(PG8_SA(1, 0), a3, voffA);
;             PG8_WAIT_V(8); PG8_WAIT_L(0); PG8_BAR; PG8_MMA(1, 0, At, B0); PG8_MMA(1, 1, At, B1); PG8_BAR; PG8_SCHED;
	s_add_i32 s33, s33, s43
	v_lshl_add_u64 v[232:233], v[232:233], 0, s[10:11]
	s_mov_b32 m0, s33
	ds_read_b128 v[200:203], v170 offset:49152
	ds_read_b128 v[204:207], v170 offset:50176
	ds_read_b128 v[208:211], v170 offset:51200
	ds_read_b128 v[212:215], v170 offset:52224
	ds_read_b128 v[216:219], v170 offset:53248
	ds_read_b128 v[220:223], v170 offset:54272
	ds_read_b128 v[224:227], v170 offset:55296
	ds_read_b128 v[228:231], v170 offset:56320
	global_load_lds_dwordx4 v[232:233], off
	s_add_i32 m0, s33, 0x2000
	s_add_u32 s38, s38, 0x80080
	v_lshl_add_u64 v[232:233], v[234:235], 0, s[10:11]
	s_addc_u32 s39, s39, 0
	s_add_i32 s33, s63, s43
	global_load_lds_dwordx4 v[232:233], off
	s_mov_b32 m0, s33
	v_lshl_add_u64 v[232:233], s[38:39], 0, v[134:135]
	global_load_lds_dwordx4 v[232:233], off
	s_add_i32 m0, s33, 0x2000
	v_lshl_add_u64 v[232:233], s[38:39], 0, v[138:139]
	global_load_lds_dwordx4 v[232:233], off
	s_waitcnt vmcnt(6) lgkmcnt(0)
	s_barrier
	s_setprio 1
	v_mfma_f32_16x16x32_bf16 v[62:65], v[148:151], v[200:203], v[62:65]
	v_mfma_f32_16x16x32_bf16 v[58:61], v[176:179], v[200:203], v[58:61]
	v_mfma_f32_16x16x32_bf16 v[46:49], v[148:151], v[208:211], v[46:49]
	v_mfma_f32_16x16x32_bf16 v[42:45], v[176:179], v[208:211], v[42:45]
	v_mfma_f32_16x16x32_bf16 v[30:33], v[148:151], v[216:219], v[30:33]
	v_mfma_f32_16x16x32_bf16 v[26:29], v[176:179], v[216:219], v[26:29]
	v_mfma_f32_16x16x32_bf16 v[14:17], v[148:151], v[224:227], v[14:17]
	v_mfma_f32_16x16x32_bf16 v[10:13], v[176:179], v[224:227], v[10:13]
	v_mfma_f32_16x16x32_bf16 v[62:65], v[172:175], v[204:207], v[62:65]
	v_mfma_f32_16x16x32_bf16 v[58:61], v[180:183], v[204:207], v[58:61]
	v_mfma_f32_16x16x32_bf16 v[46:49], v[172:175], v[212:215], v[46:49]
	v_mfma_f32_16x16x32_bf16 v[42:45], v[180:183], v[212:215], v[42:45]
	v_mfma_f32_16x16x32_bf16 v[30:33], v[172:175], v[220:223], v[30:33]
	v_mfma_f32_16x16x32_bf16 v[26:29], v[180:183], v[220:223], v[26:29]
	v_mfma_f32_16x16x32_bf16 v[14:17], v[172:175], v[228:231], v[14:17]
	v_mfma_f32_16x16x32_bf16 v[10:13], v[180:183], v[228:231], v[10:13]
	s_setprio 0
	s_setprio 1
	v_mfma_f32_16x16x32_bf16 v[54:57], v[184:187], v[200:203], v[54:57]
	s_add_i32 s62, s62, 2
	v_mfma_f32_16x16x32_bf16 v[50:53], v[192:195], v[200:203], v[50:53]
	s_add_u32 s36, s36, 0x100
	v_mfma_f32_16x16x32_bf16 v[38:41], v[184:187], v[208:211], v[38:41]
	s_addc_u32 s37, s37, 0
	v_mfma_f32_16x16x32_bf16 v[34:37], v[192:195], v[208:211], v[34:37]
	s_add_u32 s60, s60, 0x100
	v_mfma_f32_16x16x32_bf16 v[22:25], v[184:187], v[216:219], v[22:25]
	s_addc_u32 s61, s61, 0
	v_mfma_f32_16x16x32_bf16 v[18:21], v[192:195], v[216:219], v[18:21]
	s_add_u32 s33, s36, 0xfff80080
	v_mfma_f32_16x16x32_bf16 v[6:9], v[184:187], v[224:227], v[6:9]
	s_addc_u32 s38, s37, -1
	v_mfma_f32_16x16x32_bf16 v[2:5], v[192:195], v[224:227], v[2:5]
	s_cmp_eq_u32 s62, 28
	v_mfma_f32_16x16x32_bf16 v[54:57], v[188:191], v[204:207], v[54:57]
	s_cselect_b32 s41, s25, s38
	v_mfma_f32_16x16x32_bf16 v[50:53], v[196:199], v[204:207], v[50:53]
	s_cselect_b32 s40, s58, s33
	v_mfma_f32_16x16x32_bf16 v[38:41], v[188:191], v[212:215], v[38:41]
	s_cselect_b32 s39, s23, s61
	v_mfma_f32_16x16x32_bf16 v[34:37], v[196:199], v[212:215], v[34:37]
	s_cselect_b32 s38, s59, s60
	v_mfma_f32_16x16x32_bf16 v[22:25], v[188:191], v[220:223], v[22:25]
	s_add_u32 s98, s36, 0xfff80000
	v_mfma_f32_16x16x32_bf16 v[18:21], v[196:199], v[220:223], v[18:21]
	s_addc_u32 s99, s37, -1
	v_mfma_f32_16x16x32_bf16 v[6:9], v[188:191], v[228:231], v[6:9]
	s_cmp_gt_u32 s62, 29
	v_mfma_f32_16x16x32_bf16 v[2:5], v[196:199], v[228:231], v[2:5]
	s_setprio 0
	s_barrier
	s_cbranch_scc0 .LBB0_497
	s_and_b64 vcc, exec, s[12:13]
	s_cbranch_vccz .LBB0_500
	s_barrier

; template <class Epi, class Sched, bool ALIGN_EPI = false, bool SP2 = false, bool KSEG = false>
; __device__ __forceinline__ void gemm_phase(PG8_LAS unsigned char* lds, const Gemm g, const Sched& S, const Epi& E) {
;     ...
;         for (int t = 0; t < nt; t += 2) {
;             const bool last = (t == nt - 2);
;             const char* a1 = cA + (size_t)(t + 1) * kstep;
;             const char* a2 = last ? nA : cA + (size_t)(t + 2) * kstep; const char* b2 = last ? nB : cB + (size_t)(t + 2) * kstep;
;             const char* a3 = a2 + kstep; const char* b3 = b2 + kstep;
;     ...
; #pragma unroll
;         for (int a = 0; a < 2; ++a)
; #pragma unroll
;             for (int b = 0; b < 2; ++b)
; #pragma unroll
;                 for (int m = 0; m < 4; ++m)
; #pragma unroll
;                     for (int n = 0; n < 2; ++n) acc[a][b][m][n] = (f32x4){0.f, 0.f, 0.f, 0.f};
;         cur = nxt; cA = nA; cB = nB; ++ui;
.LBB0_536:
	s_add_u32 s36, s36, 0x160080
	s_addc_u32 s37, s37, 0
	s_add_u32 s62, s38, 0x100
	v_mov_b32_e32 v2, 0
	s_addc_u32 s63, s39, 0
	s_mov_b32 s64, -2
	v_mov_b32_e32 v3, v2
	v_mov_b32_e32 v4, v2
	v_mov_b32_e32 v5, v2
	v_mov_b32_e32 v6, v2
	v_mov_b32_e32 v7, v2
	v_mov_b32_e32 v8, v2
	v_mov_b32_e32 v9, v2
	v_mov_b32_e32 v18, v2
	v_mov_b32_e32 v19, v2
	v_mov_b32_e32 v20, v2
	v_mov_b32_e32 v21, v2
	v_mov_b32_e32 v22, v2
	v_mov_b32_e32 v23, v2
	v_mov_b32_e32 v24, v2
	v_mov_b32_e32 v25, v2
	v_mov_b32_e32 v34, v2
	v_mov_b32_e32 v35, v2
	v_mov_b32_e32 v36, v2
	v_mov_b32_e32 v37, v2
	v_mov_b32_e32 v38, v2
	s_waitcnt lgkmcnt(0)
	v_mov_b32_e32 v39, v2
	v_mov_b32_e32 v40, v2
	v_mov_b32_e32 v41, v2
	v_mov_b32_e32 v50, v2
	v_mov_b32_e32 v51, v2
	v_mov_b32_e32 v52, v2
	v_mov_b32_e32 v53, v2
	v_mov_b32_e32 v54, v2
	v_mov_b32_e32 v55, v2
	v_mov_b32_e32 v56, v2
	v_mov_b32_e32 v57, v2
	v_mov_b32_e32 v10, v2
	v_mov_b32_e32 v11, v2
	v_mov_b32_e32 v12, v2
	v_mov_b32_e32 v13, v2
	v_mov_b32_e32 v14, v2
	v_mov_b32_e32 v15, v2
	v_mov_b32_e32 v16, v2
	v_mov_b32_e32 v17, v2
	v_mov_b32_e32 v26, v2
	v_mov_b32_e32 v27, v2
	v_mov_b32_e32 v28, v2
	v_mov_b32_e32 v29, v2
	v_mov_b32_e32 v30, v2
	v_mov_b32_e32 v31, v2
	v_mov_b32_e32 v32, v2
	v_mov_b32_e32 v33, v2
	v_mov_b32_e32 v42, v2
	v_mov_b32_e32 v43, v2
	v_mov_b32_e32 v44, v2
	v_mov_b32_e32 v45, v2
	v_mov_b32_e32 v46, v2
	v_mov_b32_e32 v47, v2
	v_mov_b32_e32 v48, v2
	v_mov_b32_e32 v49, v2
	v_mov_b32_e32 v58, v2
	v_mov_b32_e32 v59, v2
	v_mov_b32_e32 v60, v2
	v_mov_b32_e32 v61, v2
	v_mov_b32_e32 v62, v2
	v_mov_b32_e32 v63, v2
	v_mov_b32_e32 v64, v2
	v_mov_b32_e32 v65, v2
	v_mov_b32_e32 v66, v2
	v_mov_b32_e32 v67, v2
	v_mov_b32_e32 v68, v2
	v_mov_b32_e32 v69, v2
	v_mov_b32_e32 v70, v2
	v_mov_b32_e32 v71, v2
	v_mov_b32_e32 v72, v2
	v_mov_b32_e32 v73, v2
	v_mov_b32_e32 v82, v2
	v_mov_b32_e32 v83, v2
	v_mov_b32_e32 v84, v2
	v_mov_b32_e32 v85, v2
	v_mov_b32_e32 v86, v2
	v_mov_b32_e32 v87, v2
	v_mov_b32_e32 v88, v2
	v_mov_b32_e32 v89, v2
	v_mov_b32_e32 v98, v2
	v_mov_b32_e32 v99, v2
	v_mov_b32_e32 v100, v2
	v_mov_b32_e32 v101, v2
	v_mov_b32_e32 v102, v2
	v_mov_b32_e32 v103, v2
	v_mov_b32_e32 v104, v2
	v_mov_b32_e32 v105, v2
	v_mov_b32_e32 v114, v2
	v_mov_b32_e32 v115, v2
	v_mov_b32_e32 v116, v2
	v_mov_b32_e32 v117, v2
	v_mov_b32_e32 v118, v2
	v_mov_b32_e32 v119, v2
	v_mov_b32_e32 v120, v2
	v_mov_b32_e32 v121, v2
	v_mov_b32_e32 v74, v2
	v_mov_b32_e32 v75, v2
	v_mov_b32_e32 v76, v2
	v_mov_b32_e32 v77, v2
	v_mov_b32_e32 v78, v2
	v_mov_b32_e32 v79, v2
	v_mov_b32_e32 v80, v2
	v_mov_b32_e32 v81, v2
	v_mov_b32_e32 v90, v2
	v_mov_b32_e32 v91, v2
	v_mov_b32_e32 v92, v2
	v_mov_b32_e32 v93, v2
	v_mov_b32_e32 v94, v2
	v_mov_b32_e32 v95, v2
	v_mov_b32_e32 v96, v2
	v_mov_b32_e32 v97, v2
	v_mov_b32_e32 v106, v2
	v_mov_b32_e32 v107, v2
	v_mov_b32_e32 v108, v2
	v_mov_b32_e32 v109, v2
	v_mov_b32_e32 v110, v2
	v_mov_b32_e32 v111, v2
	v_mov_b32_e32 v112, v2
	v_mov_b32_e32 v113, v2
	v_mov_b32_e32 v122, v2
	v_mov_b32_e32 v123, v2
	v_mov_b32_e32 v124, v2
	v_mov_b32_e32 v125, v2
	v_mov_b32_e32 v126, v2
	v_mov_b32_e32 v127, v2
	v_mov_b32_e32 v128, v2
	v_mov_b32_e32 v129, v2
	s_add_u32 s33, s36, 0xffea0080
	s_addc_u32 s38, s37, -1
	s_cmpk_eq_i32 s64, 0x54
	s_cselect_b32 s41, s13, s38
	s_cselect_b32 s40, s12, s33
	s_cselect_b32 s39, s31, s63
	s_cselect_b32 s38, s30, s62
	s_add_u32 s98, s36, 0xffea0000
	s_addc_u32 s99, s37, -1
	v_add_u32_e32 v250, 0x18000, v171
	v_add_u32_e32 v251, 0x1c000, v171
.LBB0_537:
	ds_read_b128 v[154:157], v173
	ds_read_b128 v[176:179], v173 offset:1024
	ds_read_b128 v[180:183], v173 offset:2048
	ds_read_b128 v[184:187], v173 offset:3072
	ds_read_b128 v[188:191], v174
	ds_read_b128 v[192:195], v174 offset:1024
	ds_read_b128 v[196:199], v174 offset:2048
	ds_read_b128 v[200:203], v174 offset:3072
	s_mov_b32 m0, s54
	v_lshl_add_u64 v[236:237], s[98:99], 0, v[140:141]
	global_load_lds_dwordx4 v[236:237], off
	s_mov_b32 m0, s55
	v_lshl_add_u64 v[236:237], s[98:99], 0, v[142:143]
	global_load_lds_dwordx4 v[236:237], off
	v_lshl_add_u64 v[236:237], s[36:37], 0, v[146:147]
	s_add_i32 m0, s44, 0xc000
	ds_read_b128 v[204:207], v175
	ds_read_b128 v[208:211], v175 offset:1024
	ds_read_b128 v[212:215], v175 offset:2048
	ds_read_b128 v[216:219], v175 offset:3072
	ds_read_b128 v[220:223], v175 offset:4096
	ds_read_b128 v[224:227], v175 offset:5120
	ds_read_b128 v[228:231], v175 offset:6144
	ds_read_b128 v[232:235], v175 offset:7168
	global_load_lds_dwordx4 v[236:237], off
	s_add_i32 m0, s44, 0xe000
	v_lshl_add_u64 v[236:237], s[36:37], 0, v[148:149]
	global_load_lds_dwordx4 v[236:237], off
	s_waitcnt vmcnt(8) lgkmcnt(0)
	s_barrier
; #define PG8_STAGE(bufoff, gbase, voff) do { _Pragma("unroll") for (int _i = 0; _i < 2; ++_i) \
;         __builtin_amdgcn_global_load_lds((const unsigned*)((const char*)(gbase) + (voff)[_i]), (PG8_LAS unsigned*)(lds + (bufoff) + ldsw + _i * 8192), 16, 0, 0); } while (0)
; #define PG8_LDA(dst, b, h) do { _Pragma("unroll") for (int m = 0; m < 4; ++m) _Pragma("unroll") for (int k = 0; k < 2; ++k) dst[m][k] = *(const PG8_LAS bf16x8*)(lds + PG8_SA(b, h) + aoff + m * 2048 + k * 1024); } while (0)
; #define PG8_LDB(dst, b, h) do { _Pragma("unroll") for (int n = 0; n < 2; ++n) _Pragma("unroll") for (int k = 0; k < 2; ++k) dst[n][k] = *(const PG8_LAS bf16x8*)(lds + PG8_SB(b, h) + boff + n * 2048 + k * 1024); } while (0)
; #define PG8_MMA(ai, bj, At, Bt) do { __builtin_amdgcn_s_setprio(1); _Pragma("unroll") for (int m = 0; m < 4; ++m) _Pragma("unroll") for (int n = 0; n < 2; ++n) _Pragma("unroll") for (int k = 0; k < 2; ++k) \
;         acc[ai][bj][m][n] = __builtin_amdgcn_mfma_f32_16x16x32_bf16(Bt[n][k], At[m][k], acc[ai][bj][m][n], 0, 0, 0); __builtin_amdgcn_s_setprio(0); } while (0)
; #define PG8_WAIT_V(n) asm volatile("s_waitcnt vmcnt(" #n ")" ::: "memory")
; #define PG8_WAIT_L(n) asm volatile("s_waitcnt lgkmcnt(" #n ")" ::: "memory")
; #define PG8_BAR __builtin_amdgcn_s_barrier()
; #define PG8_SCHED __builtin_amdgcn_sched_barrier(0)
; template <class Epi, class Sched, bool ALIGN_EPI = false, bool SP2 = false, bool KSEG = false>
; __device__ __forceinline__ void gemm_phase(PG8_LAS unsigned char* lds, const Gemm g, const Sched& S, const Epi& E) {
;     ...
;             PG8_LDB(B0, 0, 0); PG8_LDB(B1, 0, 1); PG8_SCHED; PG8_LDA(At, 0, 0); PG8_STAGE(PG8_SA(1, 1), a1 + hstep, voffA);
;             PG8_WAIT_V(8); PG8_WAIT_L(0); PG8_BAR; PG8_MMA(0, 0, At, B0); PG8_MMA(0, 1, At, B1); PG8_BAR; PG8_SCHED;
;             PG8_LDA(At, 0, 1); PG8_STAGE(PG8_SB(0, 0), b2, voffB); PG8_STAGE(PG8_SB(0, 1), b2 + hstep, voffB); PG8_STAGE(PG8_SA(0, 0), a2, voffA);
;             PG8_WAIT_V(8); PG8_WAIT_L(0); PG8_BAR; PG8_MMA(1, 0, At, B0); PG8_MMA(1, 1, At, B1); PG8_BAR; PG8_SCHED;
	s_setprio 1
	v_mfma_f32_16x16x32_bf16 v[126:129], v[154:157], v[204:207], v[126:129]
	v_mfma_f32_16x16x32_bf16 v[122:125], v[180:183], v[204:207], v[122:125]
	v_mfma_f32_16x16x32_bf16 v[110:113], v[154:157], v[212:215], v[110:113]
	v_mfma_f32_16x16x32_bf16 v[106:109], v[180:183], v[212:215], v[106:109]
	v_mfma_f32_16x16x32_bf16 v[94:97], v[154:157], v[220:223], v[94:97]
	v_mfma_f32_16x16x32_bf16 v[90:93], v[180:183], v[220:223], v[90:93]
	v_mfma_f32_16x16x32_bf16 v[78:81], v[154:157], v[228:231], v[78:81]
	v_mfma_f32_16x16x32_bf16 v[74:77], v[180:183], v[228:231], v[74:77]
	v_mfma_f32_16x16x32_bf16 v[126:129], v[176:179], v[208:211], v[126:129]
	v_mfma_f32_16x16x32_bf16 v[122:125], v[184:187], v[208:211], v[122:125]
	v_mfma_f32_16x16x32_bf16 v[110:113], v[176:179], v[216:219], v[110:113]
	v_mfma_f32_16x16x32_bf16 v[106:109], v[184:187], v[216:219], v[106:109]
	v_mfma_f32_16x16x32_bf16 v[94:97], v[176:179], v[224:227], v[94:97]
	v_mfma_f32_16x16x32_bf16 v[90:93], v[184:187], v[224:227], v[90:93]
	v_mfma_f32_16x16x32_bf16 v[78:81], v[176:179], v[232:235], v[78:81]
	v_mfma_f32_16x16x32_bf16 v[74:77], v[184:187], v[232:235], v[74:77]
	s_setprio 0
	s_setprio 1
	v_mfma_f32_16x16x32_bf16 v[118:121], v[188:191], v[204:207], v[118:121]
	v_mfma_f32_16x16x32_bf16 v[114:117], v[196:199], v[204:207], v[114:117]
	v_mfma_f32_16x16x32_bf16 v[102:105], v[188:191], v[212:215], v[102:105]
	v_mfma_f32_16x16x32_bf16 v[98:101], v[196:199], v[212:215], v[98:101]
	v_mfma_f32_16x16x32_bf16 v[86:89], v[188:191], v[220:223], v[86:89]
	v_mfma_f32_16x16x32_bf16 v[82:85], v[196:199], v[220:223], v[82:85]
	v_mfma_f32_16x16x32_bf16 v[70:73], v[188:191], v[228:231], v[70:73]
	v_mfma_f32_16x16x32_bf16 v[66:69], v[196:199], v[228:231], v[66:69]
	v_mfma_f32_16x16x32_bf16 v[118:121], v[192:195], v[208:211], v[118:121]
	v_mfma_f32_16x16x32_bf16 v[114:117], v[200:203], v[208:211], v[114:117]
	v_mfma_f32_16x16x32_bf16 v[102:105], v[192:195], v[216:219], v[102:105]
	v_mfma_f32_16x16x32_bf16 v[98:101], v[200:203], v[216:219], v[98:101]
	v_mfma_f32_16x16x32_bf16 v[86:89], v[192:195], v[224:227], v[86:89]
	v_mfma_f32_16x16x32_bf16 v[82:85], v[200:203], v[224:227], v[82:85]
	v_mfma_f32_16x16x32_bf16 v[70:73], v[192:195], v[232:235], v[70:73]
	v_mfma_f32_16x16x32_bf16 v[66:69], v[200:203], v[232:235], v[66:69]
	s_setprio 0
	s_barrier
	s_add_i32 s33, s56, s43
	v_lshl_add_u64 v[236:237], s[38:39], 0, v[130:131]
	s_mov_b32 m0, s33
	ds_read_b128 v[204:207], v175 offset:16384
	ds_read_b128 v[208:211], v175 offset:17408
	ds_read_b128 v[212:215], v175 offset:18432
	ds_read_b128 v[216:219], v175 offset:19456
	ds_read_b128 v[220:223], v175 offset:20480
	ds_read_b128 v[224:227], v175 offset:21504
	ds_read_b128 v[228:231], v175 offset:22528
	ds_read_b128 v[232:235], v175 offset:23552
	global_load_lds_dwordx4 v[236:237], off
	s_add_i32 m0, s33, 0x2000
	s_add_u32 s66, s38, 0x160000
	v_lshl_add_u64 v[238:239], s[38:39], 0, v[144:145]
	s_addc_u32 s67, s39, 0
	s_add_i32 s33, s57, s43
	global_load_lds_dwordx4 v[238:239], off
	s_mov_b32 m0, s33
	v_lshl_add_u64 v[240:241], s[66:67], 0, v[130:131]
	global_load_lds_dwordx4 v[240:241], off
	s_add_i32 m0, s33, 0x2000
	v_lshl_add_u64 v[240:241], s[66:67], 0, v[144:145]
	global_load_lds_dwordx4 v[240:241], off
	s_waitcnt vmcnt(6) lgkmcnt(0)
	s_barrier
	s_setprio 1
	v_mfma_f32_16x16x32_bf16 v[62:65], v[154:157], v[204:207], v[62:65]
	v_mfma_f32_16x16x32_bf16 v[58:61], v[180:183], v[204:207], v[58:61]
	v_mfma_f32_16x16x32_bf16 v[46:49], v[154:157], v[212:215], v[46:49]
	v_mfma_f32_16x16x32_bf16 v[42:45], v[180:183], v[212:215], v[42:45]
	v_mfma_f32_16x16x32_bf16 v[30:33], v[154:157], v[220:223], v[30:33]
	v_mfma_f32_16x16x32_bf16 v[26:29], v[180:183], v[220:223], v[26:29]
	v_mfma_f32_16x16x32_bf16 v[14:17], v[154:157], v[228:231], v[14:17]
	v_mfma_f32_16x16x32_bf16 v[10:13], v[180:183], v[228:231], v[10:13]
	v_mfma_f32_16x16x32_bf16 v[62:65], v[176:179], v[208:211], v[62:65]
	v_mfma_f32_16x16x32_bf16 v[58:61], v[184:187], v[208:211], v[58:61]
	v_mfma_f32_16x16x32_bf16 v[46:49], v[176:179], v[216:219], v[46:49]
	v_mfma_f32_16x16x32_bf16 v[42:45], v[184:187], v[216:219], v[42:45]
	v_mfma_f32_16x16x32_bf16 v[30:33], v[176:179], v[224:227], v[30:33]
	v_mfma_f32_16x16x32_bf16 v[26:29], v[184:187], v[224:227], v[26:29]
	v_mfma_f32_16x16x32_bf16 v[14:17], v[176:179], v[232:235], v[14:17]
	v_mfma_f32_16x16x32_bf16 v[10:13], v[184:187], v[232:235], v[10:13]
	s_setprio 0
	s_setprio 1
	v_mfma_f32_16x16x32_bf16 v[54:57], v[188:191], v[204:207], v[54:57]
	v_mfma_f32_16x16x32_bf16 v[50:53], v[196:199], v[204:207], v[50:53]
	v_mfma_f32_16x16x32_bf16 v[38:41], v[188:191], v[212:215], v[38:41]
	v_mfma_f32_16x16x32_bf16 v[34:37], v[196:199], v[212:215], v[34:37]
	v_mfma_f32_16x16x32_bf16 v[22:25], v[188:191], v[220:223], v[22:25]
	v_mfma_f32_16x16x32_bf16 v[18:21], v[196:199], v[220:223], v[18:21]
	v_mfma_f32_16x16x32_bf16 v[6:9], v[188:191], v[228:231], v[6:9]
	v_mfma_f32_16x16x32_bf16 v[2:5], v[196:199], v[228:231], v[2:5]
	v_mfma_f32_16x16x32_bf16 v[54:57], v[192:195], v[208:211], v[54:57]
	v_mfma_f32_16x16x32_bf16 v[50:53], v[200:203], v[208:211], v[50:53]
	v_mfma_f32_16x16x32_bf16 v[38:41], v[192:195], v[216:219], v[38:41]
	v_mfma_f32_16x16x32_bf16 v[34:37], v[200:203], v[216:219], v[34:37]
	v_mfma_f32_16x16x32_bf16 v[22:25], v[192:195], v[224:227], v[22:25]
	v_mfma_f32_16x16x32_bf16 v[18:21], v[200:203], v[224:227], v[18:21]
	v_mfma_f32_16x16x32_bf16 v[6:9], v[192:195], v[232:235], v[6:9]
	v_mfma_f32_16x16x32_bf16 v[2:5], v[200:203], v[232:235], v[2:5]
	s_setprio 0
	s_barrier
; #define PG8_STAGE(bufoff, gbase, voff) do { _Pragma("unroll") for (int _i = 0; _i < 2; ++_i) \
;         __builtin_amdgcn_global_load_lds((const unsigned*)((const char*)(gbase) + (voff)[_i]), (PG8_LAS unsigned*)(lds + (bufoff) + ldsw + _i * 8192), 16, 0, 0); } while (0)
; #define PG8_LDA(dst, b, h) do { _Pragma("unroll") for (int m = 0; m < 4; ++m) _Pragma("unroll") for (int k = 0; k < 2; ++k) dst[m][k] = *(const PG8_LAS bf16x8*)(lds + PG8_SA(b, h) + aoff + m * 2048 + k * 1024); } while (0)
; #define PG8_LDB(dst, b, h) do { _Pragma("unroll") for (int n = 0; n < 2; ++n) _Pragma("unroll") for (int k = 0; k < 2; ++k) dst[n][k] = *(const PG8_LAS bf16x8*)(lds + PG8_SB(b, h) + boff + n * 2048 + k * 1024); } while (0)
; #define PG8_MMA(ai, bj, At, Bt) do { __builtin_amdgcn_s_setprio(1); _Pragma("unroll") for (int m = 0; m < 4; ++m) _Pragma("unroll") for (int n = 0; n < 2; ++n) _Pragma("unroll") for (int k = 0; k < 2; ++k) \
;         acc[ai][bj][m][n] = __builtin_amdgcn_mfma_f32_16x16x32_bf16(Bt[n][k], At[m][k], acc[ai][bj][m][n], 0, 0, 0); __builtin_amdgcn_s_setprio(0); } while (0)
; #define PG8_WAIT_V(n) asm volatile("s_waitcnt vmcnt(" #n ")" ::: "memory")
; #define PG8_WAIT_L(n) asm volatile("s_waitcnt lgkmcnt(" #n ")" ::: "memory")
; #define PG8_BAR __builtin_amdgcn_s_barrier()
; #define PG8_SCHED __builtin_amdgcn_sched_barrier(0)
; template <class Epi, class Sched, bool ALIGN_EPI = false, bool SP2 = false, bool KSEG = false>
; __device__ __forceinline__ void gemm_phase(PG8_LAS unsigned char* lds, const Gemm g, const Sched& S, const Epi& E) {
;     ...
;             PG8_LDB(B0, 1, 0); PG8_LDB(B1, 1, 1); PG8_SCHED; PG8_LDA(At, 1, 0); PG8_STAGE(PG8_SA(0, 1), a2 + hstep, voffA);
;             PG8_WAIT_V(8); PG8_WAIT_L(0); PG8_BAR; PG8_MMA(0, 0, At, B0); PG8_MMA(0, 1, At, B1); PG8_BAR; PG8_SCHED;
	s_add_i32 s33, 0, 0x18000
	s_add_i32 s65, 0, 0x1c000
	ds_read_b128 v[154:157], v250
	ds_read_b128 v[176:179], v250 offset:1024
	ds_read_b128 v[180:183], v250 offset:2048
	ds_read_b128 v[184:187], v250 offset:3072
	ds_read_b128 v[188:191], v251
	ds_read_b128 v[192:195], v251 offset:1024
	ds_read_b128 v[196:199], v251 offset:2048
	ds_read_b128 v[200:203], v251 offset:3072
	s_mov_b32 m0, s44
	v_lshl_add_u64 v[244:245], s[40:41], 0, v[140:141]
	global_load_lds_dwordx4 v[244:245], off
	s_mov_b32 m0, s45
	v_lshl_add_u64 v[244:245], s[40:41], 0, v[142:143]
	global_load_lds_dwordx4 v[244:245], off
	s_add_u32 s40, s40, 0x160000
	s_addc_u32 s41, s41, 0
	s_mov_b32 m0, s51
	v_lshl_add_u64 v[244:245], s[40:41], 0, v[140:141]
	ds_read_b128 v[204:207], v175 offset:32768
	ds_read_b128 v[208:211], v175 offset:33792
	ds_read_b128 v[212:215], v175 offset:34816
	ds_read_b128 v[216:219], v175 offset:35840
	ds_read_b128 v[220:223], v175 offset:36864
	ds_read_b128 v[224:227], v175 offset:37888
	ds_read_b128 v[228:231], v175 offset:38912
	ds_read_b128 v[232:235], v175 offset:39936
	global_load_lds_dwordx4 v[244:245], off
	s_mov_b32 m0, s52
	v_lshl_add_u64 v[244:245], s[40:41], 0, v[142:143]
	global_load_lds_dwordx4 v[244:245], off
	s_waitcnt vmcnt(8) lgkmcnt(0)
	s_barrier
	s_setprio 1
	v_mfma_f32_16x16x32_bf16 v[126:129], v[154:157], v[204:207], v[126:129]
	v_mfma_f32_16x16x32_bf16 v[122:125], v[180:183], v[204:207], v[122:125]
	v_mfma_f32_16x16x32_bf16 v[110:113], v[154:157], v[212:215], v[110:113]
	v_mfma_f32_16x16x32_bf16 v[106:109], v[180:183], v[212:215], v[106:109]
	v_mfma_f32_16x16x32_bf16 v[94:97], v[154:157], v[220:223], v[94:97]
	v_mfma_f32_16x16x32_bf16 v[90:93], v[180:183], v[220:223], v[90:93]
	v_mfma_f32_16x16x32_bf16 v[78:81], v[154:157], v[228:231], v[78:81]
	v_mfma_f32_16x16x32_bf16 v[74:77], v[180:183], v[228:231], v[74:77]
	v_mfma_f32_16x16x32_bf16 v[126:129], v[176:179], v[208:211], v[126:129]
	v_mfma_f32_16x16x32_bf16 v[122:125], v[184:187], v[208:211], v[122:125]
	v_mfma_f32_16x16x32_bf16 v[110:113], v[176:179], v[216:219], v[110:113]
	v_mfma_f32_16x16x32_bf16 v[106:109], v[184:187], v[216:219], v[106:109]
	v_mfma_f32_16x16x32_bf16 v[94:97], v[176:179], v[224:227], v[94:97]
	v_mfma_f32_16x16x32_bf16 v[90:93], v[184:187], v[224:227], v[90:93]
	v_mfma_f32_16x16x32_bf16 v[78:81], v[176:179], v[232:235], v[78:81]
	v_mfma_f32_16x16x32_bf16 v[74:77], v[184:187], v[232:235], v[74:77]
	s_setprio 0
	s_setprio 1
	v_mfma_f32_16x16x32_bf16 v[118:121], v[188:191], v[204:207], v[118:121]
	v_mfma_f32_16x16x32_bf16 v[114:117], v[196:199], v[204:207], v[114:117]
	v_mfma_f32_16x16x32_bf16 v[102:105], v[188:191], v[212:215], v[102:105]
	v_mfma_f32_16x16x32_bf16 v[98:101], v[196:199], v[212:215], v[98:101]
	v_mfma_f32_16x16x32_bf16 v[86:89], v[188:191], v[220:223], v[86:89]
	v_mfma_f32_16x16x32_bf16 v[82:85], v[196:199], v[220:223], v[82:85]
	v_mfma_f32_16x16x32_bf16 v[70:73], v[188:191], v[228:231], v[70:73]
	v_mfma_f32_16x16x32_bf16 v[66:69], v[196:199], v[228:231], v[66:69]
	v_mfma_f32_16x16x32_bf16 v[118:121], v[192:195], v[208:211], v[118:121]
	v_mfma_f32_16x16x32_bf16 v[114:117], v[200:203], v[208:211], v[114:117]
	v_mfma_f32_16x16x32_bf16 v[102:105], v[192:195], v[216:219], v[102:105]
	v_mfma_f32_16x16x32_bf16 v[98:101], v[200:203], v[216:219], v[98:101]
	v_mfma_f32_16x16x32_bf16 v[86:89], v[192:195], v[224:227], v[86:89]
	v_mfma_f32_16x16x32_bf16 v[82:85], v[200:203], v[224:227], v[82:85]
	v_mfma_f32_16x16x32_bf16 v[70:73], v[192:195], v[232:235], v[70:73]
	v_mfma_f32_16x16x32_bf16 v[66:69], v[200:203], v[232:235], v[66:69]
	s_setprio 0
	s_barrier
; #define PG8_STAGE(bufoff, gbase, voff) do { _Pragma("unroll") for (int _i = 0; _i < 2; ++_i) \
;         __builtin_amdgcn_global_load_lds((const unsigned*)((const char*)(gbase) + (voff)[_i]), (PG8_LAS unsigned*)(lds + (bufoff) + ldsw + _i * 8192), 16, 0, 0); } while (0)
; #define PG8_LDA(dst, b, h) do { _Pragma("unroll") for (int m = 0; m < 4; ++m) _Pragma("unroll") for (int k = 0; k < 2; ++k) dst[m][k] = *(const PG8_LAS bf16x8*)(lds + PG8_SA(b, h) + aoff + m * 2048 + k * 1024); } while (0)
; #define PG8_MMA(ai, bj, At, Bt) do { __builtin_amdgcn_s_setprio(1); _Pragma("unroll") for (int m = 0; m < 4; ++m) _Pragma("unroll") for (int n = 0; n < 2; ++n) _Pragma("unroll") for (int k = 0; k < 2; ++k) \
;         acc[ai][bj][m][n] = __builtin_amdgcn_mfma_f32_16x16x32_bf16(Bt[n][k], At[m][k], acc[ai][bj][m][n], 0, 0, 0); __builtin_amdgcn_s_setprio(0); } while (0)
; #define PG8_WAIT_V(n) asm volatile("s_waitcnt vmcnt(" #n ")" ::: "memory")
; #define PG8_WAIT_L(n) asm volatile("s_waitcnt lgkmcnt(" #n ")" ::: "memory")
; #define PG8_BAR __builtin_amdgcn_s_barrier()
; #define PG8_SCHED __builtin_amdgcn_sched_barrier(0)
; template <class Epi, class Sched, bool ALIGN_EPI = false, bool SP2 = false, bool KSEG = false>
; __device__ __forceinline__ void gemm_phase(PG8_LAS unsigned char* lds, const Gemm g, const Sched& S, const Epi& E) {
;     ...
;         for (int t = 0; t < nt; t += 2) {
;             const bool last = (t == nt - 2);
;             const char* a1 = cA + (size_t)(t + 1) * kstep;
;             const char* a2 = last ? nA : cA + (size_t)(t + 2) * kstep; const char* b2 = last ? nB : cB + (size_t)(t + 2) * kstep;
;             const char* a3 = a2 + kstep; const char* b3 = b2 + kstep;
;     ...
;             PG8_LDA(At, 1, 1); PG8_STAGE(PG8_SB(1, 0), b3, voffB); PG8_STAGE(PG8_SB(1, 1), b3 + hstep, voffB); PG8_STAGE(PG8_SA(1, 0), a3, voffA);
;             PG8_WAIT_V(8); PG8_WAIT_L(0); PG8_BAR; PG8_MMA(1, 0, At, B0); PG8_MMA(1, 1, At, B1); PG8_BAR; PG8_SCHED;
	s_add_i32 s33, s33, s43
	v_lshl_add_u64 v[236:237], v[236:237], 0, s[26:27]
	s_mov_b32 m0, s33
	ds_read_b128 v[204:207], v175 offset:49152
	ds_read_b128 v[208:211], v175 offset:50176
	ds_read_b128 v[212:215], v175 offset:51200
	ds_read_b128 v[216:219], v175 offset:52224
	ds_read_b128 v[220:223], v175 offset:53248
	ds_read_b128 v[224:227], v175 offset:54272
	ds_read_b128 v[228:231], v175 offset:55296
	ds_read_b128 v[232:235], v175 offset:56320
	global_load_lds_dwordx4 v[236:237], off
	s_add_i32 m0, s33, 0x2000
	s_add_u32 s38, s38, 0x160080
	v_lshl_add_u64 v[236:237], v[238:239], 0, s[26:27]
	s_addc_u32 s39, s39, 0
	s_add_i32 s33, s65, s43
	global_load_lds_dwordx4 v[236:237], off
	s_mov_b32 m0, s33
	v_lshl_add_u64 v[236:237], s[38:39], 0, v[130:131]
	global_load_lds_dwordx4 v[236:237], off
	s_add_i32 m0, s33, 0x2000
	v_lshl_add_u64 v[236:237], s[38:39], 0, v[144:145]
	global_load_lds_dwordx4 v[236:237], off
	s_waitcnt vmcnt(6) lgkmcnt(0)
	s_barrier
	s_setprio 1
	v_mfma_f32_16x16x32_bf16 v[62:65], v[154:157], v[204:207], v[62:65]
	v_mfma_f32_16x16x32_bf16 v[58:61], v[180:183], v[204:207], v[58:61]
	v_mfma_f32_16x16x32_bf16 v[46:49], v[154:157], v[212:215], v[46:49]
	v_mfma_f32_16x16x32_bf16 v[42:45], v[180:183], v[212:215], v[42:45]
	v_mfma_f32_16x16x32_bf16 v[30:33], v[154:157], v[220:223], v[30:33]
	v_mfma_f32_16x16x32_bf16 v[26:29], v[180:183], v[220:223], v[26:29]
	v_mfma_f32_16x16x32_bf16 v[14:17], v[154:157], v[228:231], v[14:17]
	v_mfma_f32_16x16x32_bf16 v[10:13], v[180:183], v[228:231], v[10:13]
	v_mfma_f32_16x16x32_bf16 v[62:65], v[176:179], v[208:211], v[62:65]
	v_mfma_f32_16x16x32_bf16 v[58:61], v[184:187], v[208:211], v[58:61]
	v_mfma_f32_16x16x32_bf16 v[46:49], v[176:179], v[216:219], v[46:49]
	v_mfma_f32_16x16x32_bf16 v[42:45], v[184:187], v[216:219], v[42:45]
	v_mfma_f32_16x16x32_bf16 v[30:33], v[176:179], v[224:227], v[30:33]
	v_mfma_f32_16x16x32_bf16 v[26:29], v[184:187], v[224:227], v[26:29]
	v_mfma_f32_16x16x32_bf16 v[14:17], v[176:179], v[232:235], v[14:17]
	v_mfma_f32_16x16x32_bf16 v[10:13], v[184:187], v[232:235], v[10:13]
	s_setprio 0
	s_setprio 1
	v_mfma_f32_16x16x32_bf16 v[54:57], v[188:191], v[204:207], v[54:57]
	s_add_i32 s64, s64, 2
	v_mfma_f32_16x16x32_bf16 v[50:53], v[196:199], v[204:207], v[50:53]
	s_add_u32 s36, s36, 0x100
	v_mfma_f32_16x16x32_bf16 v[38:41], v[188:191], v[212:215], v[38:41]
	s_addc_u32 s37, s37, 0
	v_mfma_f32_16x16x32_bf16 v[34:37], v[196:199], v[212:215], v[34:37]
	s_add_u32 s62, s62, 0x100
	v_mfma_f32_16x16x32_bf16 v[22:25], v[188:191], v[220:223], v[22:25]
	s_addc_u32 s63, s63, 0
	v_mfma_f32_16x16x32_bf16 v[18:21], v[196:199], v[220:223], v[18:21]
	s_add_u32 s33, s36, 0xffea0080
	v_mfma_f32_16x16x32_bf16 v[6:9], v[188:191], v[228:231], v[6:9]
	s_addc_u32 s38, s37, -1
	v_mfma_f32_16x16x32_bf16 v[2:5], v[196:199], v[228:231], v[2:5]
	s_cmpk_eq_i32 s64, 0x54
	v_mfma_f32_16x16x32_bf16 v[54:57], v[192:195], v[208:211], v[54:57]
	s_cselect_b32 s41, s13, s38
	v_mfma_f32_16x16x32_bf16 v[50:53], v[200:203], v[208:211], v[50:53]
	s_cselect_b32 s40, s12, s33
	v_mfma_f32_16x16x32_bf16 v[38:41], v[192:195], v[216:219], v[38:41]
	s_cselect_b32 s39, s31, s63
	v_mfma_f32_16x16x32_bf16 v[34:37], v[200:203], v[216:219], v[34:37]
	s_cselect_b32 s38, s30, s62
	v_mfma_f32_16x16x32_bf16 v[22:25], v[192:195], v[224:227], v[22:25]
	s_add_u32 s98, s36, 0xffea0000
	v_mfma_f32_16x16x32_bf16 v[18:21], v[200:203], v[224:227], v[18:21]
	s_addc_u32 s99, s37, -1
	v_mfma_f32_16x16x32_bf16 v[6:9], v[192:195], v[232:235], v[6:9]
	s_cmpk_gt_u32 s64, 0x55
	v_mfma_f32_16x16x32_bf16 v[2:5], v[200:203], v[232:235], v[2:5]
	s_setprio 0
	s_barrier
	s_cbranch_scc0 .LBB0_537
	s_and_b64 vcc, exec, s[28:29]
	s_cbranch_vccz .LBB0_540
	s_barrier

; #define PG8_STAGE(bufoff, gbase, voff) do { _Pragma("unroll") for (int _i = 0; _i < 2; ++_i) \
;         __builtin_amdgcn_global_load_lds((const unsigned*)((const char*)(gbase) + (voff)[_i]), (PG8_LAS unsigned*)(lds + (bufoff) + ldsw + _i * 8192), 16, 0, 0); } while (0)
; #define PG8_LDA(dst, b, h) do { _Pragma("unroll") for (int m = 0; m < 4; ++m) _Pragma("unroll") for (int k = 0; k < 2; ++k) dst[m][k] = *(const PG8_LAS bf16x8*)(lds + PG8_SA(b, h) + aoff + m * 2048 + k * 1024); } while (0)
; #define PG8_LDB(dst, b, h) do { _Pragma("unroll") for (int n = 0; n < 2; ++n) _Pragma("unroll") for (int k = 0; k < 2; ++k) dst[n][k] = *(const PG8_LAS bf16x8*)(lds + PG8_SB(b, h) + boff + n * 2048 + k * 1024); } while (0)
; #define PG8_MMA(ai, bj, At, Bt) do { __builtin_amdgcn_s_setprio(1); _Pragma("unroll") for (int m = 0; m < 4; ++m) _Pragma("unroll") for (int n = 0; n < 2; ++n) _Pragma("unroll") for (int k = 0; k < 2; ++k) \
;         acc[ai][bj][m][n] = __builtin_amdgcn_mfma_f32_16x16x32_bf16(Bt[n][k], At[m][k], acc[ai][bj][m][n], 0, 0, 0); __builtin_amdgcn_s_setprio(0); } while (0)
; #define PG8_WAIT_V(n) asm volatile("s_waitcnt vmcnt(" #n ")" ::: "memory")
; #define PG8_WAIT_L(n) asm volatile("s_waitcnt lgkmcnt(" #n ")" ::: "memory")
; #define PG8_BAR __builtin_amdgcn_s_barrier()
; #define PG8_SCHED __builtin_amdgcn_sched_barrier(0)
; template <class Epi, class Sched, bool ALIGN_EPI = false, bool SP2 = false, bool KSEG = false>
; __device__ __forceinline__ void gemm_phase(PG8_LAS unsigned char* lds, const Gemm g, const Sched& S, const Epi& E) {
;     ...
;             PG8_LDB(B0, 0, 0); PG8_LDB(B1, 0, 1); PG8_SCHED; PG8_LDA(At, 0, 0); PG8_STAGE(PG8_SA(1, 1), a1 + hstep, voffA);
;             PG8_WAIT_V(8); PG8_WAIT_L(0); PG8_BAR; PG8_MMA(0, 0, At, B0); PG8_MMA(0, 1, At, B1); PG8_BAR; PG8_SCHED;
;     ...
; #pragma unroll
;         for (int a = 0; a < 2; ++a)
; #pragma unroll
;             for (int b = 0; b < 2; ++b)
; #pragma unroll
;                 for (int m = 0; m < 4; ++m)
; #pragma unroll
;                     for (int n = 0; n < 2; ++n) acc[a][b][m][n] = (f32x4){0.f, 0.f, 0.f, 0.f};
;         cur = nxt; cA = nA; cB = nB; ++ui;
.LBB0_580:
	s_ashr_i32 s29, s28, 31
	s_lshl_b64 s[30:31], s[28:29], 20
	s_add_u32 s30, s51, s30
	v_cmp_lt_i64_e64 s[6:7], s[6:7], v[150:151]
	s_addc_u32 s31, s52, s31
	s_and_b64 s[36:37], s[6:7], exec
	s_cselect_b32 s29, s31, s41
	s_cselect_b32 s65, s30, s40
	s_ashr_i32 s27, s26, 31
	s_lshl_b64 s[36:37], s[26:27], 20
	s_add_u32 s36, s76, s36
	s_addc_u32 s37, s77, s37
	s_and_b64 s[44:45], s[6:7], exec
	s_cselect_b32 s27, s37, s43
	s_cselect_b32 s66, s36, s42
	s_add_u32 s40, s40, 0x80080
	s_addc_u32 s41, s41, 0
	s_add_u32 s67, s42, 0x100
	v_mov_b32_e32 v2, 0
	s_addc_u32 s78, s43, 0
	s_mov_b32 s79, -2
	v_mov_b32_e32 v3, v2
	v_mov_b32_e32 v4, v2
	v_mov_b32_e32 v5, v2
	v_mov_b32_e32 v6, v2
	v_mov_b32_e32 v7, v2
	v_mov_b32_e32 v8, v2
	v_mov_b32_e32 v9, v2
	v_mov_b32_e32 v18, v2
	v_mov_b32_e32 v19, v2
	v_mov_b32_e32 v20, v2
	v_mov_b32_e32 v21, v2
	v_mov_b32_e32 v22, v2
	v_mov_b32_e32 v23, v2
	v_mov_b32_e32 v24, v2
	v_mov_b32_e32 v25, v2
	v_mov_b32_e32 v34, v2
	v_mov_b32_e32 v35, v2
	v_mov_b32_e32 v36, v2
	v_mov_b32_e32 v37, v2
	v_mov_b32_e32 v38, v2
	s_waitcnt lgkmcnt(0)
	v_mov_b32_e32 v39, v2
	v_mov_b32_e32 v40, v2
	v_mov_b32_e32 v41, v2
	v_mov_b32_e32 v50, v2
	v_mov_b32_e32 v51, v2
	v_mov_b32_e32 v52, v2
	v_mov_b32_e32 v53, v2
	v_mov_b32_e32 v54, v2
	v_mov_b32_e32 v55, v2
	v_mov_b32_e32 v56, v2
	v_mov_b32_e32 v57, v2
	v_mov_b32_e32 v10, v2
	v_mov_b32_e32 v11, v2
	v_mov_b32_e32 v12, v2
	v_mov_b32_e32 v13, v2
	v_mov_b32_e32 v14, v2
	v_mov_b32_e32 v15, v2
	v_mov_b32_e32 v16, v2
	v_mov_b32_e32 v17, v2
	v_mov_b32_e32 v26, v2
	v_mov_b32_e32 v27, v2
	v_mov_b32_e32 v28, v2
	v_mov_b32_e32 v29, v2
	v_mov_b32_e32 v30, v2
	v_mov_b32_e32 v31, v2
	v_mov_b32_e32 v32, v2
	v_mov_b32_e32 v33, v2
	v_mov_b32_e32 v42, v2
	v_mov_b32_e32 v43, v2
	v_mov_b32_e32 v44, v2
	v_mov_b32_e32 v45, v2
	v_mov_b32_e32 v46, v2
	v_mov_b32_e32 v47, v2
	v_mov_b32_e32 v48, v2
	v_mov_b32_e32 v49, v2
	v_mov_b32_e32 v58, v2
	v_mov_b32_e32 v59, v2
	v_mov_b32_e32 v60, v2
	v_mov_b32_e32 v61, v2
	v_mov_b32_e32 v62, v2
	v_mov_b32_e32 v63, v2
	v_mov_b32_e32 v64, v2
	v_mov_b32_e32 v65, v2
	v_mov_b32_e32 v66, v2
	v_mov_b32_e32 v67, v2
	v_mov_b32_e32 v68, v2
	v_mov_b32_e32 v69, v2
	v_mov_b32_e32 v70, v2
	v_mov_b32_e32 v71, v2
	v_mov_b32_e32 v72, v2
	v_mov_b32_e32 v73, v2
	v_mov_b32_e32 v82, v2
	v_mov_b32_e32 v83, v2
	v_mov_b32_e32 v84, v2
	v_mov_b32_e32 v85, v2
	v_mov_b32_e32 v86, v2
	v_mov_b32_e32 v87, v2
	v_mov_b32_e32 v88, v2
	v_mov_b32_e32 v89, v2
	v_mov_b32_e32 v98, v2
	v_mov_b32_e32 v99, v2
	v_mov_b32_e32 v100, v2
	v_mov_b32_e32 v101, v2
	v_mov_b32_e32 v102, v2
	v_mov_b32_e32 v103, v2
	v_mov_b32_e32 v104, v2
	v_mov_b32_e32 v105, v2
	v_mov_b32_e32 v114, v2
	v_mov_b32_e32 v115, v2
	v_mov_b32_e32 v116, v2
	v_mov_b32_e32 v117, v2
	v_mov_b32_e32 v118, v2
	v_mov_b32_e32 v119, v2
	v_mov_b32_e32 v120, v2
	v_mov_b32_e32 v121, v2
	v_mov_b32_e32 v74, v2
	v_mov_b32_e32 v75, v2
	v_mov_b32_e32 v76, v2
	v_mov_b32_e32 v77, v2
	v_mov_b32_e32 v78, v2
	v_mov_b32_e32 v79, v2
	v_mov_b32_e32 v80, v2
	v_mov_b32_e32 v81, v2
	v_mov_b32_e32 v90, v2
	v_mov_b32_e32 v91, v2
	v_mov_b32_e32 v92, v2
	v_mov_b32_e32 v93, v2
	v_mov_b32_e32 v94, v2
	v_mov_b32_e32 v95, v2
	v_mov_b32_e32 v96, v2
	v_mov_b32_e32 v97, v2
	v_mov_b32_e32 v106, v2
	v_mov_b32_e32 v107, v2
	v_mov_b32_e32 v108, v2
	v_mov_b32_e32 v109, v2
	v_mov_b32_e32 v110, v2
	v_mov_b32_e32 v111, v2
	v_mov_b32_e32 v112, v2
	v_mov_b32_e32 v113, v2
	v_mov_b32_e32 v122, v2
	v_mov_b32_e32 v123, v2
	v_mov_b32_e32 v124, v2
	v_mov_b32_e32 v125, v2
	v_mov_b32_e32 v126, v2
	v_mov_b32_e32 v127, v2
	v_mov_b32_e32 v128, v2
	v_mov_b32_e32 v129, v2
	s_add_u32 s33, s40, 0xfff80080
	s_addc_u32 s42, s41, -1
	s_cmp_eq_u32 s79, 28
	s_cselect_b32 s45, s29, s42
	s_cselect_b32 s44, s65, s33
	s_cselect_b32 s43, s27, s78
	s_cselect_b32 s42, s66, s67
	s_add_u32 s98, s40, 0xfff80000
	s_addc_u32 s99, s41, -1
	v_add_u32_e32 v250, 0x18000, v163
	v_add_u32_e32 v251, 0x1c000, v163
.LBB0_581:
	ds_read_b128 v[154:157], v160
	ds_read_b128 v[172:175], v160 offset:1024
	ds_read_b128 v[176:179], v160 offset:2048
	ds_read_b128 v[180:183], v160 offset:3072
	ds_read_b128 v[184:187], v161
	ds_read_b128 v[188:191], v161 offset:1024
	ds_read_b128 v[192:195], v161 offset:2048
	ds_read_b128 v[196:199], v161 offset:3072
	s_mov_b32 m0, s60
	v_lshl_add_u64 v[232:233], s[98:99], 0, v[132:133]
	global_load_lds_dwordx4 v[232:233], off
	s_mov_b32 m0, s61
	v_lshl_add_u64 v[232:233], s[98:99], 0, v[136:137]
	global_load_lds_dwordx4 v[232:233], off
	v_lshl_add_u64 v[232:233], s[40:41], 0, v[146:147]
	s_add_i32 m0, s55, 0xc000
	ds_read_b128 v[200:203], v164
	ds_read_b128 v[204:207], v164 offset:1024
	ds_read_b128 v[208:211], v164 offset:2048
	ds_read_b128 v[212:215], v164 offset:3072
	ds_read_b128 v[216:219], v164 offset:4096
	ds_read_b128 v[220:223], v164 offset:5120
	ds_read_b128 v[224:227], v164 offset:6144
	ds_read_b128 v[228:231], v164 offset:7168
	global_load_lds_dwordx4 v[232:233], off
	s_add_i32 m0, s55, 0xe000
	v_lshl_add_u64 v[232:233], s[40:41], 0, v[148:149]
	global_load_lds_dwordx4 v[232:233], off
	s_waitcnt vmcnt(8) lgkmcnt(0)
	s_barrier
; #define PG8_STAGE(bufoff, gbase, voff) do { _Pragma("unroll") for (int _i = 0; _i < 2; ++_i) \
;         __builtin_amdgcn_global_load_lds((const unsigned*)((const char*)(gbase) + (voff)[_i]), (PG8_LAS unsigned*)(lds + (bufoff) + ldsw + _i * 8192), 16, 0, 0); } while (0)
; #define PG8_LDA(dst, b, h) do { _Pragma("unroll") for (int m = 0; m < 4; ++m) _Pragma("unroll") for (int k = 0; k < 2; ++k) dst[m][k] = *(const PG8_LAS bf16x8*)(lds + PG8_SA(b, h) + aoff + m * 2048 + k * 1024); } while (0)
; #define PG8_MMA(ai, bj, At, Bt) do { __builtin_amdgcn_s_setprio(1); _Pragma("unroll") for (int m = 0; m < 4; ++m) _Pragma("unroll") for (int n = 0; n < 2; ++n) _Pragma("unroll") for (int k = 0; k < 2; ++k) \
;         acc[ai][bj][m][n] = __builtin_amdgcn_mfma_f32_16x16x32_bf16(Bt[n][k], At[m][k], acc[ai][bj][m][n], 0, 0, 0); __builtin_amdgcn_s_setprio(0); } while (0)
; #define PG8_WAIT_V(n) asm volatile("s_waitcnt vmcnt(" #n ")" ::: "memory")
; #define PG8_WAIT_L(n) asm volatile("s_waitcnt lgkmcnt(" #n ")" ::: "memory")
; #define PG8_BAR __builtin_amdgcn_s_barrier()
; #define PG8_SCHED __builtin_amdgcn_sched_barrier(0)
; template <class Epi, class Sched, bool ALIGN_EPI = false, bool SP2 = false, bool KSEG = false>
; __device__ __forceinline__ void gemm_phase(PG8_LAS unsigned char* lds, const Gemm g, const Sched& S, const Epi& E) {
;     ...
;             PG8_WAIT_V(8); PG8_WAIT_L(0); PG8_BAR; PG8_MMA(0, 0, At, B0); PG8_MMA(0, 1, At, B1); PG8_BAR; PG8_SCHED;
;             PG8_LDA(At, 0, 1); PG8_STAGE(PG8_SB(0, 0), b2, voffB); PG8_STAGE(PG8_SB(0, 1), b2 + hstep, voffB); PG8_STAGE(PG8_SA(0, 0), a2, voffA);
;             PG8_WAIT_V(8); PG8_WAIT_L(0); PG8_BAR; PG8_MMA(1, 0, At, B0); PG8_MMA(1, 1, At, B1); PG8_BAR; PG8_SCHED;
	s_setprio 1
	v_mfma_f32_16x16x32_bf16 v[126:129], v[154:157], v[200:203], v[126:129]
	v_mfma_f32_16x16x32_bf16 v[122:125], v[176:179], v[200:203], v[122:125]
	v_mfma_f32_16x16x32_bf16 v[110:113], v[154:157], v[208:211], v[110:113]
	v_mfma_f32_16x16x32_bf16 v[106:109], v[176:179], v[208:211], v[106:109]
	v_mfma_f32_16x16x32_bf16 v[94:97], v[154:157], v[216:219], v[94:97]
	v_mfma_f32_16x16x32_bf16 v[90:93], v[176:179], v[216:219], v[90:93]
	v_mfma_f32_16x16x32_bf16 v[78:81], v[154:157], v[224:227], v[78:81]
	v_mfma_f32_16x16x32_bf16 v[74:77], v[176:179], v[224:227], v[74:77]
	v_mfma_f32_16x16x32_bf16 v[126:129], v[172:175], v[204:207], v[126:129]
	v_mfma_f32_16x16x32_bf16 v[122:125], v[180:183], v[204:207], v[122:125]
	v_mfma_f32_16x16x32_bf16 v[110:113], v[172:175], v[212:215], v[110:113]
	v_mfma_f32_16x16x32_bf16 v[106:109], v[180:183], v[212:215], v[106:109]
	v_mfma_f32_16x16x32_bf16 v[94:97], v[172:175], v[220:223], v[94:97]
	v_mfma_f32_16x16x32_bf16 v[90:93], v[180:183], v[220:223], v[90:93]
	v_mfma_f32_16x16x32_bf16 v[78:81], v[172:175], v[228:231], v[78:81]
	v_mfma_f32_16x16x32_bf16 v[74:77], v[180:183], v[228:231], v[74:77]
	s_setprio 0
	s_setprio 1
	v_mfma_f32_16x16x32_bf16 v[118:121], v[184:187], v[200:203], v[118:121]
	v_mfma_f32_16x16x32_bf16 v[114:117], v[192:195], v[200:203], v[114:117]
	v_mfma_f32_16x16x32_bf16 v[102:105], v[184:187], v[208:211], v[102:105]
	v_mfma_f32_16x16x32_bf16 v[98:101], v[192:195], v[208:211], v[98:101]
	v_mfma_f32_16x16x32_bf16 v[86:89], v[184:187], v[216:219], v[86:89]
	v_mfma_f32_16x16x32_bf16 v[82:85], v[192:195], v[216:219], v[82:85]
	v_mfma_f32_16x16x32_bf16 v[70:73], v[184:187], v[224:227], v[70:73]
	v_mfma_f32_16x16x32_bf16 v[66:69], v[192:195], v[224:227], v[66:69]
	v_mfma_f32_16x16x32_bf16 v[118:121], v[188:191], v[204:207], v[118:121]
	v_mfma_f32_16x16x32_bf16 v[114:117], v[196:199], v[204:207], v[114:117]
	v_mfma_f32_16x16x32_bf16 v[102:105], v[188:191], v[212:215], v[102:105]
	v_mfma_f32_16x16x32_bf16 v[98:101], v[196:199], v[212:215], v[98:101]
	v_mfma_f32_16x16x32_bf16 v[86:89], v[188:191], v[220:223], v[86:89]
	v_mfma_f32_16x16x32_bf16 v[82:85], v[196:199], v[220:223], v[82:85]
	v_mfma_f32_16x16x32_bf16 v[70:73], v[188:191], v[228:231], v[70:73]
	v_mfma_f32_16x16x32_bf16 v[66:69], v[196:199], v[228:231], v[66:69]
	s_setprio 0
	s_barrier
	s_add_i32 s33, s62, s53
	v_lshl_add_u64 v[232:233], s[42:43], 0, v[134:135]
	s_mov_b32 m0, s33
	ds_read_b128 v[200:203], v164 offset:16384
	ds_read_b128 v[204:207], v164 offset:17408
	ds_read_b128 v[208:211], v164 offset:18432
	ds_read_b128 v[212:215], v164 offset:19456
	ds_read_b128 v[216:219], v164 offset:20480
	ds_read_b128 v[220:223], v164 offset:21504
	ds_read_b128 v[224:227], v164 offset:22528
	ds_read_b128 v[228:231], v164 offset:23552
	global_load_lds_dwordx4 v[232:233], off
	s_add_i32 m0, s33, 0x2000
	s_add_u32 s80, s42, 0x80000
	v_lshl_add_u64 v[234:235], s[42:43], 0, v[138:139]
	s_addc_u32 s81, s43, 0
	s_add_i32 s33, s63, s53
	global_load_lds_dwordx4 v[234:235], off
	s_mov_b32 m0, s33
	v_lshl_add_u64 v[236:237], s[80:81], 0, v[134:135]
	global_load_lds_dwordx4 v[236:237], off
	s_add_i32 m0, s33, 0x2000
	v_lshl_add_u64 v[236:237], s[80:81], 0, v[138:139]
	global_load_lds_dwordx4 v[236:237], off
	s_waitcnt vmcnt(6) lgkmcnt(0)
	s_barrier
	s_setprio 1
	v_mfma_f32_16x16x32_bf16 v[62:65], v[154:157], v[200:203], v[62:65]
	v_mfma_f32_16x16x32_bf16 v[58:61], v[176:179], v[200:203], v[58:61]
	v_mfma_f32_16x16x32_bf16 v[46:49], v[154:157], v[208:211], v[46:49]
	v_mfma_f32_16x16x32_bf16 v[42:45], v[176:179], v[208:211], v[42:45]
	v_mfma_f32_16x16x32_bf16 v[30:33], v[154:157], v[216:219], v[30:33]
	v_mfma_f32_16x16x32_bf16 v[26:29], v[176:179], v[216:219], v[26:29]
	v_mfma_f32_16x16x32_bf16 v[14:17], v[154:157], v[224:227], v[14:17]
	v_mfma_f32_16x16x32_bf16 v[10:13], v[176:179], v[224:227], v[10:13]
	v_mfma_f32_16x16x32_bf16 v[62:65], v[172:175], v[204:207], v[62:65]
	v_mfma_f32_16x16x32_bf16 v[58:61], v[180:183], v[204:207], v[58:61]
	v_mfma_f32_16x16x32_bf16 v[46:49], v[172:175], v[212:215], v[46:49]
	v_mfma_f32_16x16x32_bf16 v[42:45], v[180:183], v[212:215], v[42:45]
	v_mfma_f32_16x16x32_bf16 v[30:33], v[172:175], v[220:223], v[30:33]
	v_mfma_f32_16x16x32_bf16 v[26:29], v[180:183], v[220:223], v[26:29]
	v_mfma_f32_16x16x32_bf16 v[14:17], v[172:175], v[228:231], v[14:17]
	v_mfma_f32_16x16x32_bf16 v[10:13], v[180:183], v[228:231], v[10:13]
	s_setprio 0
	s_setprio 1
	v_mfma_f32_16x16x32_bf16 v[54:57], v[184:187], v[200:203], v[54:57]
	v_mfma_f32_16x16x32_bf16 v[50:53], v[192:195], v[200:203], v[50:53]
	v_mfma_f32_16x16x32_bf16 v[38:41], v[184:187], v[208:211], v[38:41]
	v_mfma_f32_16x16x32_bf16 v[34:37], v[192:195], v[208:211], v[34:37]
	v_mfma_f32_16x16x32_bf16 v[22:25], v[184:187], v[216:219], v[22:25]
	v_mfma_f32_16x16x32_bf16 v[18:21], v[192:195], v[216:219], v[18:21]
	v_mfma_f32_16x16x32_bf16 v[6:9], v[184:187], v[224:227], v[6:9]
	v_mfma_f32_16x16x32_bf16 v[2:5], v[192:195], v[224:227], v[2:5]
	v_mfma_f32_16x16x32_bf16 v[54:57], v[188:191], v[204:207], v[54:57]
	v_mfma_f32_16x16x32_bf16 v[50:53], v[196:199], v[204:207], v[50:53]
	v_mfma_f32_16x16x32_bf16 v[38:41], v[188:191], v[212:215], v[38:41]
	v_mfma_f32_16x16x32_bf16 v[34:37], v[196:199], v[212:215], v[34:37]
	v_mfma_f32_16x16x32_bf16 v[22:25], v[188:191], v[220:223], v[22:25]
	v_mfma_f32_16x16x32_bf16 v[18:21], v[196:199], v[220:223], v[18:21]
	v_mfma_f32_16x16x32_bf16 v[6:9], v[188:191], v[228:231], v[6:9]
	v_mfma_f32_16x16x32_bf16 v[2:5], v[196:199], v[228:231], v[2:5]
	s_setprio 0
	s_barrier
; #define PG8_STAGE(bufoff, gbase, voff) do { _Pragma("unroll") for (int _i = 0; _i < 2; ++_i) \
;         __builtin_amdgcn_global_load_lds((const unsigned*)((const char*)(gbase) + (voff)[_i]), (PG8_LAS unsigned*)(lds + (bufoff) + ldsw + _i * 8192), 16, 0, 0); } while (0)
; #define PG8_LDA(dst, b, h) do { _Pragma("unroll") for (int m = 0; m < 4; ++m) _Pragma("unroll") for (int k = 0; k < 2; ++k) dst[m][k] = *(const PG8_LAS bf16x8*)(lds + PG8_SA(b, h) + aoff + m * 2048 + k * 1024); } while (0)
; #define PG8_LDB(dst, b, h) do { _Pragma("unroll") for (int n = 0; n < 2; ++n) _Pragma("unroll") for (int k = 0; k < 2; ++k) dst[n][k] = *(const PG8_LAS bf16x8*)(lds + PG8_SB(b, h) + boff + n * 2048 + k * 1024); } while (0)
; #define PG8_MMA(ai, bj, At, Bt) do { __builtin_amdgcn_s_setprio(1); _Pragma("unroll") for (int m = 0; m < 4; ++m) _Pragma("unroll") for (int n = 0; n < 2; ++n) _Pragma("unroll") for (int k = 0; k < 2; ++k) \
;         acc[ai][bj][m][n] = __builtin_amdgcn_mfma_f32_16x16x32_bf16(Bt[n][k], At[m][k], acc[ai][bj][m][n], 0, 0, 0); __builtin_amdgcn_s_setprio(0); } while (0)
; #define PG8_WAIT_V(n) asm volatile("s_waitcnt vmcnt(" #n ")" ::: "memory")
; #define PG8_WAIT_L(n) asm volatile("s_waitcnt lgkmcnt(" #n ")" ::: "memory")
; #define PG8_BAR __builtin_amdgcn_s_barrier()
; #define PG8_SCHED __builtin_amdgcn_sched_barrier(0)
; template <class Epi, class Sched, bool ALIGN_EPI = false, bool SP2 = false, bool KSEG = false>
; __device__ __forceinline__ void gemm_phase(PG8_LAS unsigned char* lds, const Gemm g, const Sched& S, const Epi& E) {
;     ...
;             PG8_LDB(B0, 1, 0); PG8_LDB(B1, 1, 1); PG8_SCHED; PG8_LDA(At, 1, 0); PG8_STAGE(PG8_SA(0, 1), a2 + hstep, voffA);
;             PG8_WAIT_V(8); PG8_WAIT_L(0); PG8_BAR; PG8_MMA(0, 0, At, B0); PG8_MMA(0, 1, At, B1); PG8_BAR; PG8_SCHED;
	s_add_i32 s33, 0, 0x18000
	s_add_i32 s80, 0, 0x1c000
	ds_read_b128 v[154:157], v250
	ds_read_b128 v[172:175], v250 offset:1024
	ds_read_b128 v[176:179], v250 offset:2048
	ds_read_b128 v[180:183], v250 offset:3072
	ds_read_b128 v[184:187], v251
	ds_read_b128 v[188:191], v251 offset:1024
	ds_read_b128 v[192:195], v251 offset:2048
	ds_read_b128 v[196:199], v251 offset:3072
	s_mov_b32 m0, s55
	v_lshl_add_u64 v[240:241], s[44:45], 0, v[132:133]
	global_load_lds_dwordx4 v[240:241], off
	s_mov_b32 m0, s56
	v_lshl_add_u64 v[240:241], s[44:45], 0, v[136:137]
	global_load_lds_dwordx4 v[240:241], off
	s_add_u32 s44, s44, 0x80000
	s_addc_u32 s45, s45, 0
	s_mov_b32 m0, s57
	v_lshl_add_u64 v[240:241], s[44:45], 0, v[132:133]
	ds_read_b128 v[200:203], v164 offset:32768
	ds_read_b128 v[204:207], v164 offset:33792
	ds_read_b128 v[208:211], v164 offset:34816
	ds_read_b128 v[212:215], v164 offset:35840
	ds_read_b128 v[216:219], v164 offset:36864
	ds_read_b128 v[220:223], v164 offset:37888
	ds_read_b128 v[224:227], v164 offset:38912
	ds_read_b128 v[228:231], v164 offset:39936
	global_load_lds_dwordx4 v[240:241], off
	s_mov_b32 m0, s58
	v_lshl_add_u64 v[240:241], s[44:45], 0, v[136:137]
	global_load_lds_dwordx4 v[240:241], off
	s_waitcnt vmcnt(8) lgkmcnt(0)
	s_barrier
	s_setprio 1
	v_mfma_f32_16x16x32_bf16 v[126:129], v[154:157], v[200:203], v[126:129]
	v_mfma_f32_16x16x32_bf16 v[122:125], v[176:179], v[200:203], v[122:125]
	v_mfma_f32_16x16x32_bf16 v[110:113], v[154:157], v[208:211], v[110:113]
	v_mfma_f32_16x16x32_bf16 v[106:109], v[176:179], v[208:211], v[106:109]
	v_mfma_f32_16x16x32_bf16 v[94:97], v[154:157], v[216:219], v[94:97]
	v_mfma_f32_16x16x32_bf16 v[90:93], v[176:179], v[216:219], v[90:93]
	v_mfma_f32_16x16x32_bf16 v[78:81], v[154:157], v[224:227], v[78:81]
	v_mfma_f32_16x16x32_bf16 v[74:77], v[176:179], v[224:227], v[74:77]
	v_mfma_f32_16x16x32_bf16 v[126:129], v[172:175], v[204:207], v[126:129]
	v_mfma_f32_16x16x32_bf16 v[122:125], v[180:183], v[204:207], v[122:125]
	v_mfma_f32_16x16x32_bf16 v[110:113], v[172:175], v[212:215], v[110:113]
	v_mfma_f32_16x16x32_bf16 v[106:109], v[180:183], v[212:215], v[106:109]
	v_mfma_f32_16x16x32_bf16 v[94:97], v[172:175], v[220:223], v[94:97]
	v_mfma_f32_16x16x32_bf16 v[90:93], v[180:183], v[220:223], v[90:93]
	v_mfma_f32_16x16x32_bf16 v[78:81], v[172:175], v[228:231], v[78:81]
	v_mfma_f32_16x16x32_bf16 v[74:77], v[180:183], v[228:231], v[74:77]
	s_setprio 0
	s_setprio 1
	v_mfma_f32_16x16x32_bf16 v[118:121], v[184:187], v[200:203], v[118:121]
	v_mfma_f32_16x16x32_bf16 v[114:117], v[192:195], v[200:203], v[114:117]
	v_mfma_f32_16x16x32_bf16 v[102:105], v[184:187], v[208:211], v[102:105]
	v_mfma_f32_16x16x32_bf16 v[98:101], v[192:195], v[208:211], v[98:101]
	v_mfma_f32_16x16x32_bf16 v[86:89], v[184:187], v[216:219], v[86:89]
	v_mfma_f32_16x16x32_bf16 v[82:85], v[192:195], v[216:219], v[82:85]
	v_mfma_f32_16x16x32_bf16 v[70:73], v[184:187], v[224:227], v[70:73]
	v_mfma_f32_16x16x32_bf16 v[66:69], v[192:195], v[224:227], v[66:69]
	v_mfma_f32_16x16x32_bf16 v[118:121], v[188:191], v[204:207], v[118:121]
	v_mfma_f32_16x16x32_bf16 v[114:117], v[196:199], v[204:207], v[114:117]
	v_mfma_f32_16x16x32_bf16 v[102:105], v[188:191], v[212:215], v[102:105]
	v_mfma_f32_16x16x32_bf16 v[98:101], v[196:199], v[212:215], v[98:101]
	v_mfma_f32_16x16x32_bf16 v[86:89], v[188:191], v[220:223], v[86:89]
	v_mfma_f32_16x16x32_bf16 v[82:85], v[196:199], v[220:223], v[82:85]
	v_mfma_f32_16x16x32_bf16 v[70:73], v[188:191], v[228:231], v[70:73]
	v_mfma_f32_16x16x32_bf16 v[66:69], v[196:199], v[228:231], v[66:69]
	s_setprio 0
	s_barrier
; #define PG8_STAGE(bufoff, gbase, voff) do { _Pragma("unroll") for (int _i = 0; _i < 2; ++_i) \
;         __builtin_amdgcn_global_load_lds((const unsigned*)((const char*)(gbase) + (voff)[_i]), (PG8_LAS unsigned*)(lds + (bufoff) + ldsw + _i * 8192), 16, 0, 0); } while (0)
; #define PG8_LDA(dst, b, h) do { _Pragma("unroll") for (int m = 0; m < 4; ++m) _Pragma("unroll") for (int k = 0; k < 2; ++k) dst[m][k] = *(const PG8_LAS bf16x8*)(lds + PG8_SA(b, h) + aoff + m * 2048 + k * 1024); } while (0)
; #define PG8_MMA(ai, bj, At, Bt) do { __builtin_amdgcn_s_setprio(1); _Pragma("unroll") for (int m = 0; m < 4; ++m) _Pragma("unroll") for (int n = 0; n < 2; ++n) _Pragma("unroll") for (int k = 0; k < 2; ++k) \
;         acc[ai][bj][m][n] = __builtin_amdgcn_mfma_f32_16x16x32_bf16(Bt[n][k], At[m][k], acc[ai][bj][m][n], 0, 0, 0); __builtin_amdgcn_s_setprio(0); } while (0)
; #define PG8_WAIT_V(n) asm volatile("s_waitcnt vmcnt(" #n ")" ::: "memory")
; #define PG8_WAIT_L(n) asm volatile("s_waitcnt lgkmcnt(" #n ")" ::: "memory")
; #define PG8_BAR __builtin_amdgcn_s_barrier()
; #define PG8_SCHED __builtin_amdgcn_sched_barrier(0)
; template <class Epi, class Sched, bool ALIGN_EPI = false, bool SP2 = false, bool KSEG = false>
; __device__ __forceinline__ void gemm_phase(PG8_LAS unsigned char* lds, const Gemm g, const Sched& S, const Epi& E) {
;     ...
;         for (int t = 0; t < nt; t += 2) {
;             const bool last = (t == nt - 2);
;             const char* a1 = cA + (size_t)(t + 1) * kstep;
;             const char* a2 = last ? nA : cA + (size_t)(t + 2) * kstep; const char* b2 = last ? nB : cB + (size_t)(t + 2) * kstep;
;             const char* a3 = a2 + kstep; const char* b3 = b2 + kstep;
;     ...
;             PG8_LDA(At, 1, 1); PG8_STAGE(PG8_SB(1, 0), b3, voffB); PG8_STAGE(PG8_SB(1, 1), b3 + hstep, voffB); PG8_STAGE(PG8_SA(1, 0), a3, voffA);
;             PG8_WAIT_V(8); PG8_WAIT_L(0); PG8_BAR; PG8_MMA(1, 0, At, B0); PG8_MMA(1, 1, At, B1); PG8_BAR; PG8_SCHED;
	s_add_i32 s33, s33, s53
	v_lshl_add_u64 v[232:233], v[232:233], 0, s[12:13]
	s_mov_b32 m0, s33
	ds_read_b128 v[200:203], v164 offset:49152
	ds_read_b128 v[204:207], v164 offset:50176
	ds_read_b128 v[208:211], v164 offset:51200
	ds_read_b128 v[212:215], v164 offset:52224
	ds_read_b128 v[216:219], v164 offset:53248
	ds_read_b128 v[220:223], v164 offset:54272
	ds_read_b128 v[224:227], v164 offset:55296
	ds_read_b128 v[228:231], v164 offset:56320
	global_load_lds_dwordx4 v[232:233], off
	s_add_i32 m0, s33, 0x2000
	s_add_u32 s42, s42, 0x80080
	v_lshl_add_u64 v[232:233], v[234:235], 0, s[12:13]
	s_addc_u32 s43, s43, 0
	s_add_i32 s33, s80, s53
	global_load_lds_dwordx4 v[232:233], off
	s_mov_b32 m0, s33
	v_lshl_add_u64 v[232:233], s[42:43], 0, v[134:135]
	global_load_lds_dwordx4 v[232:233], off
	s_add_i32 m0, s33, 0x2000
	v_lshl_add_u64 v[232:233], s[42:43], 0, v[138:139]
	global_load_lds_dwordx4 v[232:233], off
	s_waitcnt vmcnt(6) lgkmcnt(0)
	s_barrier
	s_setprio 1
	v_mfma_f32_16x16x32_bf16 v[62:65], v[154:157], v[200:203], v[62:65]
	v_mfma_f32_16x16x32_bf16 v[58:61], v[176:179], v[200:203], v[58:61]
	v_mfma_f32_16x16x32_bf16 v[46:49], v[154:157], v[208:211], v[46:49]
	v_mfma_f32_16x16x32_bf16 v[42:45], v[176:179], v[208:211], v[42:45]
	v_mfma_f32_16x16x32_bf16 v[30:33], v[154:157], v[216:219], v[30:33]
	v_mfma_f32_16x16x32_bf16 v[26:29], v[176:179], v[216:219], v[26:29]
	v_mfma_f32_16x16x32_bf16 v[14:17], v[154:157], v[224:227], v[14:17]
	v_mfma_f32_16x16x32_bf16 v[10:13], v[176:179], v[224:227], v[10:13]
	v_mfma_f32_16x16x32_bf16 v[62:65], v[172:175], v[204:207], v[62:65]
	v_mfma_f32_16x16x32_bf16 v[58:61], v[180:183], v[204:207], v[58:61]
	v_mfma_f32_16x16x32_bf16 v[46:49], v[172:175], v[212:215], v[46:49]
	v_mfma_f32_16x16x32_bf16 v[42:45], v[180:183], v[212:215], v[42:45]
	v_mfma_f32_16x16x32_bf16 v[30:33], v[172:175], v[220:223], v[30:33]
	v_mfma_f32_16x16x32_bf16 v[26:29], v[180:183], v[220:223], v[26:29]
	v_mfma_f32_16x16x32_bf16 v[14:17], v[172:175], v[228:231], v[14:17]
	v_mfma_f32_16x16x32_bf16 v[10:13], v[180:183], v[228:231], v[10:13]
	s_setprio 0
	s_setprio 1
	v_mfma_f32_16x16x32_bf16 v[54:57], v[184:187], v[200:203], v[54:57]
	s_add_i32 s79, s79, 2
	v_mfma_f32_16x16x32_bf16 v[50:53], v[192:195], v[200:203], v[50:53]
	s_add_u32 s40, s40, 0x100
	v_mfma_f32_16x16x32_bf16 v[38:41], v[184:187], v[208:211], v[38:41]
	s_addc_u32 s41, s41, 0
	v_mfma_f32_16x16x32_bf16 v[34:37], v[192:195], v[208:211], v[34:37]
	s_add_u32 s67, s67, 0x100
	v_mfma_f32_16x16x32_bf16 v[22:25], v[184:187], v[216:219], v[22:25]
	s_addc_u32 s78, s78, 0
	v_mfma_f32_16x16x32_bf16 v[18:21], v[192:195], v[216:219], v[18:21]
	s_add_u32 s33, s40, 0xfff80080
	v_mfma_f32_16x16x32_bf16 v[6:9], v[184:187], v[224:227], v[6:9]
	s_addc_u32 s42, s41, -1
	v_mfma_f32_16x16x32_bf16 v[2:5], v[192:195], v[224:227], v[2:5]
	s_cmp_eq_u32 s79, 28
	v_mfma_f32_16x16x32_bf16 v[54:57], v[188:191], v[204:207], v[54:57]
	s_cselect_b32 s45, s29, s42
	v_mfma_f32_16x16x32_bf16 v[50:53], v[196:199], v[204:207], v[50:53]
	s_cselect_b32 s44, s65, s33
	v_mfma_f32_16x16x32_bf16 v[38:41], v[188:191], v[212:215], v[38:41]
	s_cselect_b32 s43, s27, s78
	v_mfma_f32_16x16x32_bf16 v[34:37], v[196:199], v[212:215], v[34:37]
	s_cselect_b32 s42, s66, s67
	v_mfma_f32_16x16x32_bf16 v[22:25], v[188:191], v[220:223], v[22:25]
	s_add_u32 s98, s40, 0xfff80000
	v_mfma_f32_16x16x32_bf16 v[18:21], v[196:199], v[220:223], v[18:21]
	s_addc_u32 s99, s41, -1
	v_mfma_f32_16x16x32_bf16 v[6:9], v[188:191], v[228:231], v[6:9]
	s_cmp_lt_u32 s79, 30
	v_mfma_f32_16x16x32_bf16 v[2:5], v[196:199], v[228:231], v[2:5]
	s_setprio 0
	s_barrier
	s_cbranch_scc1 .LBB0_581
	s_andn2_b64 vcc, exec, s[24:25]
	s_cbranch_vccnz .LBB0_584
	s_barrier

; #define PG8_STAGE(bufoff, gbase, voff) do { _Pragma("unroll") for (int _i = 0; _i < 2; ++_i) \
;         __builtin_amdgcn_global_load_lds((const unsigned*)((const char*)(gbase) + (voff)[_i]), (PG8_LAS unsigned*)(lds + (bufoff) + ldsw + _i * 8192), 16, 0, 0); } while (0)
; #define PG8_LDA(dst, b, h) do { _Pragma("unroll") for (int m = 0; m < 4; ++m) _Pragma("unroll") for (int k = 0; k < 2; ++k) dst[m][k] = *(const PG8_LAS bf16x8*)(lds + PG8_SA(b, h) + aoff + m * 2048 + k * 1024); } while (0)
; #define PG8_LDB(dst, b, h) do { _Pragma("unroll") for (int n = 0; n < 2; ++n) _Pragma("unroll") for (int k = 0; k < 2; ++k) dst[n][k] = *(const PG8_LAS bf16x8*)(lds + PG8_SB(b, h) + boff + n * 2048 + k * 1024); } while (0)
; #define PG8_MMA(ai, bj, At, Bt) do { __builtin_amdgcn_s_setprio(1); _Pragma("unroll") for (int m = 0; m < 4; ++m) _Pragma("unroll") for (int n = 0; n < 2; ++n) _Pragma("unroll") for (int k = 0; k < 2; ++k) \
;         acc[ai][bj][m][n] = __builtin_amdgcn_mfma_f32_16x16x32_bf16(Bt[n][k], At[m][k], acc[ai][bj][m][n], 0, 0, 0); __builtin_amdgcn_s_setprio(0); } while (0)
; #define PG8_WAIT_V(n) asm volatile("s_waitcnt vmcnt(" #n ")" ::: "memory")
; #define PG8_WAIT_L(n) asm volatile("s_waitcnt lgkmcnt(" #n ")" ::: "memory")
; #define PG8_BAR __builtin_amdgcn_s_barrier()
; #define PG8_SCHED __builtin_amdgcn_sched_barrier(0)
; template <class Epi, class Sched, bool ALIGN_EPI = false, bool SP2 = false, bool KSEG = false>
; __device__ __forceinline__ void gemm_phase(PG8_LAS unsigned char* lds, const Gemm g, const Sched& S, const Epi& E) {
;     ...
;             PG8_LDB(B0, 0, 0); PG8_LDB(B1, 0, 1); PG8_SCHED; PG8_LDA(At, 0, 0); PG8_STAGE(PG8_SA(1, 1), a1 + hstep, voffA);
;             PG8_WAIT_V(8); PG8_WAIT_L(0); PG8_BAR; PG8_MMA(0, 0, At, B0); PG8_MMA(0, 1, At, B1); PG8_BAR; PG8_SCHED;
;     ...
; #pragma unroll
;         for (int a = 0; a < 2; ++a)
; #pragma unroll
;             for (int b = 0; b < 2; ++b)
; #pragma unroll
;                 for (int m = 0; m < 4; ++m)
; #pragma unroll
;                     for (int n = 0; n < 2; ++n) acc[a][b][m][n] = (f32x4){0.f, 0.f, 0.f, 0.f};
;         cur = nxt; cA = nA; cB = nB; ++ui;
.LBB0_620:
	s_add_u32 s24, s24, 0x160080
	s_addc_u32 s25, s25, 0
	s_add_u32 s48, s26, 0x100
	v_mov_b32_e32 v2, 0
	s_addc_u32 s49, s27, 0
	s_mov_b32 s50, -2
	v_mov_b32_e32 v3, v2
	v_mov_b32_e32 v4, v2
	v_mov_b32_e32 v5, v2
	v_mov_b32_e32 v6, v2
	v_mov_b32_e32 v7, v2
	v_mov_b32_e32 v8, v2
	v_mov_b32_e32 v9, v2
	v_mov_b32_e32 v18, v2
	v_mov_b32_e32 v19, v2
	v_mov_b32_e32 v20, v2
	v_mov_b32_e32 v21, v2
	v_mov_b32_e32 v22, v2
	v_mov_b32_e32 v23, v2
	v_mov_b32_e32 v24, v2
	v_mov_b32_e32 v25, v2
	v_mov_b32_e32 v34, v2
	v_mov_b32_e32 v35, v2
	v_mov_b32_e32 v36, v2
	v_mov_b32_e32 v37, v2
	v_mov_b32_e32 v38, v2
	s_waitcnt lgkmcnt(0)
	v_mov_b32_e32 v39, v2
	v_mov_b32_e32 v40, v2
	v_mov_b32_e32 v41, v2
	v_mov_b32_e32 v50, v2
	v_mov_b32_e32 v51, v2
	v_mov_b32_e32 v52, v2
	v_mov_b32_e32 v53, v2
	v_mov_b32_e32 v54, v2
	v_mov_b32_e32 v55, v2
	v_mov_b32_e32 v56, v2
	v_mov_b32_e32 v57, v2
	v_mov_b32_e32 v10, v2
	v_mov_b32_e32 v11, v2
	v_mov_b32_e32 v12, v2
	v_mov_b32_e32 v13, v2
	v_mov_b32_e32 v14, v2
	v_mov_b32_e32 v15, v2
	v_mov_b32_e32 v16, v2
	v_mov_b32_e32 v17, v2
	v_mov_b32_e32 v26, v2
	v_mov_b32_e32 v27, v2
	v_mov_b32_e32 v28, v2
	v_mov_b32_e32 v29, v2
	v_mov_b32_e32 v30, v2
	v_mov_b32_e32 v31, v2
	v_mov_b32_e32 v32, v2
	v_mov_b32_e32 v33, v2
	v_mov_b32_e32 v42, v2
	v_mov_b32_e32 v43, v2
	v_mov_b32_e32 v44, v2
	v_mov_b32_e32 v45, v2
	v_mov_b32_e32 v46, v2
	v_mov_b32_e32 v47, v2
	v_mov_b32_e32 v48, v2
	v_mov_b32_e32 v49, v2
	v_mov_b32_e32 v58, v2
	v_mov_b32_e32 v59, v2
	v_mov_b32_e32 v60, v2
	v_mov_b32_e32 v61, v2
	v_mov_b32_e32 v62, v2
	v_mov_b32_e32 v63, v2
	v_mov_b32_e32 v64, v2
	v_mov_b32_e32 v65, v2
	v_mov_b32_e32 v66, v2
	v_mov_b32_e32 v67, v2
	v_mov_b32_e32 v68, v2
	v_mov_b32_e32 v69, v2
	v_mov_b32_e32 v70, v2
	v_mov_b32_e32 v71, v2
	v_mov_b32_e32 v72, v2
	v_mov_b32_e32 v73, v2
	v_mov_b32_e32 v82, v2
	v_mov_b32_e32 v83, v2
	v_mov_b32_e32 v84, v2
	v_mov_b32_e32 v85, v2
	v_mov_b32_e32 v86, v2
	v_mov_b32_e32 v87, v2
	v_mov_b32_e32 v88, v2
	v_mov_b32_e32 v89, v2
	v_mov_b32_e32 v98, v2
	v_mov_b32_e32 v99, v2
	v_mov_b32_e32 v100, v2
	v_mov_b32_e32 v101, v2
	v_mov_b32_e32 v102, v2
	v_mov_b32_e32 v103, v2
	v_mov_b32_e32 v104, v2
	v_mov_b32_e32 v105, v2
	v_mov_b32_e32 v114, v2
	v_mov_b32_e32 v115, v2
	v_mov_b32_e32 v116, v2
	v_mov_b32_e32 v117, v2
	v_mov_b32_e32 v118, v2
	v_mov_b32_e32 v119, v2
	v_mov_b32_e32 v120, v2
	v_mov_b32_e32 v121, v2
	v_mov_b32_e32 v74, v2
	v_mov_b32_e32 v75, v2
	v_mov_b32_e32 v76, v2
	v_mov_b32_e32 v77, v2
	v_mov_b32_e32 v78, v2
	v_mov_b32_e32 v79, v2
	v_mov_b32_e32 v80, v2
	v_mov_b32_e32 v81, v2
	v_mov_b32_e32 v90, v2
	v_mov_b32_e32 v91, v2
	v_mov_b32_e32 v92, v2
	v_mov_b32_e32 v93, v2
	v_mov_b32_e32 v94, v2
	v_mov_b32_e32 v95, v2
	v_mov_b32_e32 v96, v2
	v_mov_b32_e32 v97, v2
	v_mov_b32_e32 v106, v2
	v_mov_b32_e32 v107, v2
	v_mov_b32_e32 v108, v2
	v_mov_b32_e32 v109, v2
	v_mov_b32_e32 v110, v2
	v_mov_b32_e32 v111, v2
	v_mov_b32_e32 v112, v2
	v_mov_b32_e32 v113, v2
	v_mov_b32_e32 v122, v2
	v_mov_b32_e32 v123, v2
	v_mov_b32_e32 v124, v2
	v_mov_b32_e32 v125, v2
	v_mov_b32_e32 v126, v2
	v_mov_b32_e32 v127, v2
	v_mov_b32_e32 v128, v2
	v_mov_b32_e32 v129, v2
	s_add_u32 s26, s24, 0xffea0080
	s_addc_u32 s27, s25, -1
	s_cmpk_eq_i32 s50, 0x54
	s_cselect_b32 s29, s21, s27
	s_cselect_b32 s28, s20, s26
	s_cselect_b32 s27, s9, s49
	s_cselect_b32 s26, s8, s48
	s_add_u32 s98, s24, 0xffea0000
	s_addc_u32 s99, s25, -1
	v_add_u32_e32 v250, 0x18000, v150
	v_add_u32_e32 v251, 0x1c000, v150
.LBB0_621:
	ds_read_b128 v[146:149], v1
	ds_read_b128 v[156:159], v1 offset:1024
	ds_read_b128 v[160:163], v1 offset:2048
	ds_read_b128 v[164:167], v1 offset:3072
	ds_read_b128 v[168:171], v153
	ds_read_b128 v[172:175], v153 offset:1024
	ds_read_b128 v[176:179], v153 offset:2048
	ds_read_b128 v[180:183], v153 offset:3072
	s_mov_b32 m0, s40
	v_lshl_add_u64 v[216:217], s[98:99], 0, v[140:141]
	global_load_lds_dwordx4 v[216:217], off
	s_mov_b32 m0, s41
	v_lshl_add_u64 v[216:217], s[98:99], 0, v[142:143]
	global_load_lds_dwordx4 v[216:217], off
	v_lshl_add_u64 v[216:217], s[24:25], 0, v[132:133]
	s_add_i32 m0, s31, 0xc000
	ds_read_b128 v[184:187], v154
	ds_read_b128 v[188:191], v154 offset:1024
	ds_read_b128 v[192:195], v154 offset:2048
	ds_read_b128 v[196:199], v154 offset:3072
	ds_read_b128 v[200:203], v154 offset:4096
	ds_read_b128 v[204:207], v154 offset:5120
	ds_read_b128 v[208:211], v154 offset:6144
	ds_read_b128 v[212:215], v154 offset:7168
	global_load_lds_dwordx4 v[216:217], off
	s_add_i32 m0, s31, 0xe000
	v_lshl_add_u64 v[216:217], s[24:25], 0, v[134:135]
	global_load_lds_dwordx4 v[216:217], off
	s_waitcnt vmcnt(8) lgkmcnt(0)
	s_barrier
; #define PG8_STAGE(bufoff, gbase, voff) do { _Pragma("unroll") for (int _i = 0; _i < 2; ++_i) \
;         __builtin_amdgcn_global_load_lds((const unsigned*)((const char*)(gbase) + (voff)[_i]), (PG8_LAS unsigned*)(lds + (bufoff) + ldsw + _i * 8192), 16, 0, 0); } while (0)
; #define PG8_LDA(dst, b, h) do { _Pragma("unroll") for (int m = 0; m < 4; ++m) _Pragma("unroll") for (int k = 0; k < 2; ++k) dst[m][k] = *(const PG8_LAS bf16x8*)(lds + PG8_SA(b, h) + aoff + m * 2048 + k * 1024); } while (0)
; #define PG8_MMA(ai, bj, At, Bt) do { __builtin_amdgcn_s_setprio(1); _Pragma("unroll") for (int m = 0; m < 4; ++m) _Pragma("unroll") for (int n = 0; n < 2; ++n) _Pragma("unroll") for (int k = 0; k < 2; ++k) \
;         acc[ai][bj][m][n] = __builtin_amdgcn_mfma_f32_16x16x32_bf16(Bt[n][k], At[m][k], acc[ai][bj][m][n], 0, 0, 0); __builtin_amdgcn_s_setprio(0); } while (0)
; #define PG8_WAIT_V(n) asm volatile("s_waitcnt vmcnt(" #n ")" ::: "memory")
; #define PG8_WAIT_L(n) asm volatile("s_waitcnt lgkmcnt(" #n ")" ::: "memory")
; #define PG8_BAR __builtin_amdgcn_s_barrier()
; #define PG8_SCHED __builtin_amdgcn_sched_barrier(0)
; template <class Epi, class Sched, bool ALIGN_EPI = false, bool SP2 = false, bool KSEG = false>
; __device__ __forceinline__ void gemm_phase(PG8_LAS unsigned char* lds, const Gemm g, const Sched& S, const Epi& E) {
;     ...
;             PG8_WAIT_V(8); PG8_WAIT_L(0); PG8_BAR; PG8_MMA(0, 0, At, B0); PG8_MMA(0, 1, At, B1); PG8_BAR; PG8_SCHED;
;             PG8_LDA(At, 0, 1); PG8_STAGE(PG8_SB(0, 0), b2, voffB); PG8_STAGE(PG8_SB(0, 1), b2 + hstep, voffB); PG8_STAGE(PG8_SA(0, 0), a2, voffA);
;             PG8_WAIT_V(8); PG8_WAIT_L(0); PG8_BAR; PG8_MMA(1, 0, At, B0); PG8_MMA(1, 1, At, B1); PG8_BAR; PG8_SCHED;
	s_setprio 1
	v_mfma_f32_16x16x32_bf16 v[126:129], v[146:149], v[184:187], v[126:129]
	v_mfma_f32_16x16x32_bf16 v[122:125], v[160:163], v[184:187], v[122:125]
	v_mfma_f32_16x16x32_bf16 v[110:113], v[146:149], v[192:195], v[110:113]
	v_mfma_f32_16x16x32_bf16 v[106:109], v[160:163], v[192:195], v[106:109]
	v_mfma_f32_16x16x32_bf16 v[94:97], v[146:149], v[200:203], v[94:97]
	v_mfma_f32_16x16x32_bf16 v[90:93], v[160:163], v[200:203], v[90:93]
	v_mfma_f32_16x16x32_bf16 v[78:81], v[146:149], v[208:211], v[78:81]
	v_mfma_f32_16x16x32_bf16 v[74:77], v[160:163], v[208:211], v[74:77]
	v_mfma_f32_16x16x32_bf16 v[126:129], v[156:159], v[188:191], v[126:129]
	v_mfma_f32_16x16x32_bf16 v[122:125], v[164:167], v[188:191], v[122:125]
	v_mfma_f32_16x16x32_bf16 v[110:113], v[156:159], v[196:199], v[110:113]
	v_mfma_f32_16x16x32_bf16 v[106:109], v[164:167], v[196:199], v[106:109]
	v_mfma_f32_16x16x32_bf16 v[94:97], v[156:159], v[204:207], v[94:97]
	v_mfma_f32_16x16x32_bf16 v[90:93], v[164:167], v[204:207], v[90:93]
	v_mfma_f32_16x16x32_bf16 v[78:81], v[156:159], v[212:215], v[78:81]
	v_mfma_f32_16x16x32_bf16 v[74:77], v[164:167], v[212:215], v[74:77]
	s_setprio 0
	s_setprio 1
	v_mfma_f32_16x16x32_bf16 v[118:121], v[168:171], v[184:187], v[118:121]
	v_mfma_f32_16x16x32_bf16 v[114:117], v[176:179], v[184:187], v[114:117]
	v_mfma_f32_16x16x32_bf16 v[102:105], v[168:171], v[192:195], v[102:105]
	v_mfma_f32_16x16x32_bf16 v[98:101], v[176:179], v[192:195], v[98:101]
	v_mfma_f32_16x16x32_bf16 v[86:89], v[168:171], v[200:203], v[86:89]
	v_mfma_f32_16x16x32_bf16 v[82:85], v[176:179], v[200:203], v[82:85]
	v_mfma_f32_16x16x32_bf16 v[70:73], v[168:171], v[208:211], v[70:73]
	v_mfma_f32_16x16x32_bf16 v[66:69], v[176:179], v[208:211], v[66:69]
	v_mfma_f32_16x16x32_bf16 v[118:121], v[172:175], v[188:191], v[118:121]
	v_mfma_f32_16x16x32_bf16 v[114:117], v[180:183], v[188:191], v[114:117]
	v_mfma_f32_16x16x32_bf16 v[102:105], v[172:175], v[196:199], v[102:105]
	v_mfma_f32_16x16x32_bf16 v[98:101], v[180:183], v[196:199], v[98:101]
	v_mfma_f32_16x16x32_bf16 v[86:89], v[172:175], v[204:207], v[86:89]
	v_mfma_f32_16x16x32_bf16 v[82:85], v[180:183], v[204:207], v[82:85]
	v_mfma_f32_16x16x32_bf16 v[70:73], v[172:175], v[212:215], v[70:73]
	v_mfma_f32_16x16x32_bf16 v[66:69], v[180:183], v[212:215], v[66:69]
	s_setprio 0
	s_barrier
	s_add_i32 s33, s42, s30
	v_lshl_add_u64 v[216:217], s[26:27], 0, v[130:131]
	s_mov_b32 m0, s33
	ds_read_b128 v[184:187], v154 offset:16384
	ds_read_b128 v[188:191], v154 offset:17408
	ds_read_b128 v[192:195], v154 offset:18432
	ds_read_b128 v[196:199], v154 offset:19456
	ds_read_b128 v[200:203], v154 offset:20480
	ds_read_b128 v[204:207], v154 offset:21504
	ds_read_b128 v[208:211], v154 offset:22528
	ds_read_b128 v[212:215], v154 offset:23552
	global_load_lds_dwordx4 v[216:217], off
	s_add_i32 m0, s33, 0x2000
	s_add_u32 s54, s26, 0x160000
	v_lshl_add_u64 v[218:219], s[26:27], 0, v[144:145]
	s_addc_u32 s55, s27, 0
	s_add_i32 s33, s43, s30
	global_load_lds_dwordx4 v[218:219], off
	s_mov_b32 m0, s33
	v_lshl_add_u64 v[220:221], s[54:55], 0, v[130:131]
	global_load_lds_dwordx4 v[220:221], off
	s_add_i32 m0, s33, 0x2000
	v_lshl_add_u64 v[220:221], s[54:55], 0, v[144:145]
	global_load_lds_dwordx4 v[220:221], off
	s_waitcnt vmcnt(6) lgkmcnt(0)
	s_barrier
	s_setprio 1
	v_mfma_f32_16x16x32_bf16 v[62:65], v[146:149], v[184:187], v[62:65]
	v_mfma_f32_16x16x32_bf16 v[58:61], v[160:163], v[184:187], v[58:61]
	v_mfma_f32_16x16x32_bf16 v[46:49], v[146:149], v[192:195], v[46:49]
	v_mfma_f32_16x16x32_bf16 v[42:45], v[160:163], v[192:195], v[42:45]
	v_mfma_f32_16x16x32_bf16 v[30:33], v[146:149], v[200:203], v[30:33]
	v_mfma_f32_16x16x32_bf16 v[26:29], v[160:163], v[200:203], v[26:29]
	v_mfma_f32_16x16x32_bf16 v[14:17], v[146:149], v[208:211], v[14:17]
	v_mfma_f32_16x16x32_bf16 v[10:13], v[160:163], v[208:211], v[10:13]
	v_mfma_f32_16x16x32_bf16 v[62:65], v[156:159], v[188:191], v[62:65]
	v_mfma_f32_16x16x32_bf16 v[58:61], v[164:167], v[188:191], v[58:61]
	v_mfma_f32_16x16x32_bf16 v[46:49], v[156:159], v[196:199], v[46:49]
	v_mfma_f32_16x16x32_bf16 v[42:45], v[164:167], v[196:199], v[42:45]
	v_mfma_f32_16x16x32_bf16 v[30:33], v[156:159], v[204:207], v[30:33]
	v_mfma_f32_16x16x32_bf16 v[26:29], v[164:167], v[204:207], v[26:29]
	v_mfma_f32_16x16x32_bf16 v[14:17], v[156:159], v[212:215], v[14:17]
	v_mfma_f32_16x16x32_bf16 v[10:13], v[164:167], v[212:215], v[10:13]
	s_setprio 0
	s_setprio 1
	v_mfma_f32_16x16x32_bf16 v[54:57], v[168:171], v[184:187], v[54:57]
	v_mfma_f32_16x16x32_bf16 v[50:53], v[176:179], v[184:187], v[50:53]
	v_mfma_f32_16x16x32_bf16 v[38:41], v[168:171], v[192:195], v[38:41]
	v_mfma_f32_16x16x32_bf16 v[34:37], v[176:179], v[192:195], v[34:37]
	v_mfma_f32_16x16x32_bf16 v[22:25], v[168:171], v[200:203], v[22:25]
	v_mfma_f32_16x16x32_bf16 v[18:21], v[176:179], v[200:203], v[18:21]
	v_mfma_f32_16x16x32_bf16 v[6:9], v[168:171], v[208:211], v[6:9]
	v_mfma_f32_16x16x32_bf16 v[2:5], v[176:179], v[208:211], v[2:5]
	v_mfma_f32_16x16x32_bf16 v[54:57], v[172:175], v[188:191], v[54:57]
	v_mfma_f32_16x16x32_bf16 v[50:53], v[180:183], v[188:191], v[50:53]
	v_mfma_f32_16x16x32_bf16 v[38:41], v[172:175], v[196:199], v[38:41]
	v_mfma_f32_16x16x32_bf16 v[34:37], v[180:183], v[196:199], v[34:37]
	v_mfma_f32_16x16x32_bf16 v[22:25], v[172:175], v[204:207], v[22:25]
	v_mfma_f32_16x16x32_bf16 v[18:21], v[180:183], v[204:207], v[18:21]
	v_mfma_f32_16x16x32_bf16 v[6:9], v[172:175], v[212:215], v[6:9]
	v_mfma_f32_16x16x32_bf16 v[2:5], v[180:183], v[212:215], v[2:5]
	s_setprio 0
	s_barrier
; #define PG8_STAGE(bufoff, gbase, voff) do { _Pragma("unroll") for (int _i = 0; _i < 2; ++_i) \
;         __builtin_amdgcn_global_load_lds((const unsigned*)((const char*)(gbase) + (voff)[_i]), (PG8_LAS unsigned*)(lds + (bufoff) + ldsw + _i * 8192), 16, 0, 0); } while (0)
; #define PG8_LDA(dst, b, h) do { _Pragma("unroll") for (int m = 0; m < 4; ++m) _Pragma("unroll") for (int k = 0; k < 2; ++k) dst[m][k] = *(const PG8_LAS bf16x8*)(lds + PG8_SA(b, h) + aoff + m * 2048 + k * 1024); } while (0)
; #define PG8_LDB(dst, b, h) do { _Pragma("unroll") for (int n = 0; n < 2; ++n) _Pragma("unroll") for (int k = 0; k < 2; ++k) dst[n][k] = *(const PG8_LAS bf16x8*)(lds + PG8_SB(b, h) + boff + n * 2048 + k * 1024); } while (0)
; #define PG8_MMA(ai, bj, At, Bt) do { __builtin_amdgcn_s_setprio(1); _Pragma("unroll") for (int m = 0; m < 4; ++m) _Pragma("unroll") for (int n = 0; n < 2; ++n) _Pragma("unroll") for (int k = 0; k < 2; ++k) \
;         acc[ai][bj][m][n] = __builtin_amdgcn_mfma_f32_16x16x32_bf16(Bt[n][k], At[m][k], acc[ai][bj][m][n], 0, 0, 0); __builtin_amdgcn_s_setprio(0); } while (0)
; #define PG8_WAIT_V(n) asm volatile("s_waitcnt vmcnt(" #n ")" ::: "memory")
; #define PG8_WAIT_L(n) asm volatile("s_waitcnt lgkmcnt(" #n ")" ::: "memory")
; #define PG8_BAR __builtin_amdgcn_s_barrier()
; #define PG8_SCHED __builtin_amdgcn_sched_barrier(0)
; template <class Epi, class Sched, bool ALIGN_EPI = false, bool SP2 = false, bool KSEG = false>
; __device__ __forceinline__ void gemm_phase(PG8_LAS unsigned char* lds, const Gemm g, const Sched& S, const Epi& E) {
;     ...
;             PG8_LDB(B0, 1, 0); PG8_LDB(B1, 1, 1); PG8_SCHED; PG8_LDA(At, 1, 0); PG8_STAGE(PG8_SA(0, 1), a2 + hstep, voffA);
;             PG8_WAIT_V(8); PG8_WAIT_L(0); PG8_BAR; PG8_MMA(0, 0, At, B0); PG8_MMA(0, 1, At, B1); PG8_BAR; PG8_SCHED;
	s_add_i32 s33, 0, 0x18000
	s_add_i32 s53, 0, 0x1c000
	ds_read_b128 v[146:149], v250
	ds_read_b128 v[156:159], v250 offset:1024
	ds_read_b128 v[160:163], v250 offset:2048
	ds_read_b128 v[164:167], v250 offset:3072
	ds_read_b128 v[168:171], v251
	ds_read_b128 v[172:175], v251 offset:1024
	ds_read_b128 v[176:179], v251 offset:2048
	ds_read_b128 v[180:183], v251 offset:3072
	s_mov_b32 m0, s31
	v_lshl_add_u64 v[224:225], s[28:29], 0, v[140:141]
	global_load_lds_dwordx4 v[224:225], off
	s_mov_b32 m0, s36
	v_lshl_add_u64 v[224:225], s[28:29], 0, v[142:143]
	global_load_lds_dwordx4 v[224:225], off
	s_add_u32 s28, s28, 0x160000
	s_addc_u32 s29, s29, 0
	s_mov_b32 m0, s37
	v_lshl_add_u64 v[224:225], s[28:29], 0, v[140:141]
	ds_read_b128 v[184:187], v154 offset:32768
	ds_read_b128 v[188:191], v154 offset:33792
	ds_read_b128 v[192:195], v154 offset:34816
	ds_read_b128 v[196:199], v154 offset:35840
	ds_read_b128 v[200:203], v154 offset:36864
	ds_read_b128 v[204:207], v154 offset:37888
	ds_read_b128 v[208:211], v154 offset:38912
	ds_read_b128 v[212:215], v154 offset:39936
	global_load_lds_dwordx4 v[224:225], off
	s_mov_b32 m0, s38
	v_lshl_add_u64 v[224:225], s[28:29], 0, v[142:143]
	global_load_lds_dwordx4 v[224:225], off
	s_waitcnt vmcnt(8) lgkmcnt(0)
	s_barrier
	s_setprio 1
	v_mfma_f32_16x16x32_bf16 v[126:129], v[146:149], v[184:187], v[126:129]
	v_mfma_f32_16x16x32_bf16 v[122:125], v[160:163], v[184:187], v[122:125]
	v_mfma_f32_16x16x32_bf16 v[110:113], v[146:149], v[192:195], v[110:113]
	v_mfma_f32_16x16x32_bf16 v[106:109], v[160:163], v[192:195], v[106:109]
	v_mfma_f32_16x16x32_bf16 v[94:97], v[146:149], v[200:203], v[94:97]
	v_mfma_f32_16x16x32_bf16 v[90:93], v[160:163], v[200:203], v[90:93]
	v_mfma_f32_16x16x32_bf16 v[78:81], v[146:149], v[208:211], v[78:81]
	v_mfma_f32_16x16x32_bf16 v[74:77], v[160:163], v[208:211], v[74:77]
	v_mfma_f32_16x16x32_bf16 v[126:129], v[156:159], v[188:191], v[126:129]
	v_mfma_f32_16x16x32_bf16 v[122:125], v[164:167], v[188:191], v[122:125]
	v_mfma_f32_16x16x32_bf16 v[110:113], v[156:159], v[196:199], v[110:113]
	v_mfma_f32_16x16x32_bf16 v[106:109], v[164:167], v[196:199], v[106:109]
	v_mfma_f32_16x16x32_bf16 v[94:97], v[156:159], v[204:207], v[94:97]
	v_mfma_f32_16x16x32_bf16 v[90:93], v[164:167], v[204:207], v[90:93]
	v_mfma_f32_16x16x32_bf16 v[78:81], v[156:159], v[212:215], v[78:81]
	v_mfma_f32_16x16x32_bf16 v[74:77], v[164:167], v[212:215], v[74:77]
	s_setprio 0
	s_setprio 1
	v_mfma_f32_16x16x32_bf16 v[118:121], v[168:171], v[184:187], v[118:121]
	v_mfma_f32_16x16x32_bf16 v[114:117], v[176:179], v[184:187], v[114:117]
	v_mfma_f32_16x16x32_bf16 v[102:105], v[168:171], v[192:195], v[102:105]
	v_mfma_f32_16x16x32_bf16 v[98:101], v[176:179], v[192:195], v[98:101]
	v_mfma_f32_16x16x32_bf16 v[86:89], v[168:171], v[200:203], v[86:89]
	v_mfma_f32_16x16x32_bf16 v[82:85], v[176:179], v[200:203], v[82:85]
	v_mfma_f32_16x16x32_bf16 v[70:73], v[168:171], v[208:211], v[70:73]
	v_mfma_f32_16x16x32_bf16 v[66:69], v[176:179], v[208:211], v[66:69]
	v_mfma_f32_16x16x32_bf16 v[118:121], v[172:175], v[188:191], v[118:121]
	v_mfma_f32_16x16x32_bf16 v[114:117], v[180:183], v[188:191], v[114:117]
	v_mfma_f32_16x16x32_bf16 v[102:105], v[172:175], v[196:199], v[102:105]
	v_mfma_f32_16x16x32_bf16 v[98:101], v[180:183], v[196:199], v[98:101]
	v_mfma_f32_16x16x32_bf16 v[86:89], v[172:175], v[204:207], v[86:89]
	v_mfma_f32_16x16x32_bf16 v[82:85], v[180:183], v[204:207], v[82:85]
	v_mfma_f32_16x16x32_bf16 v[70:73], v[172:175], v[212:215], v[70:73]
	v_mfma_f32_16x16x32_bf16 v[66:69], v[180:183], v[212:215], v[66:69]
	s_setprio 0
	s_barrier
; #define PG8_STAGE(bufoff, gbase, voff) do { _Pragma("unroll") for (int _i = 0; _i < 2; ++_i) \
;         __builtin_amdgcn_global_load_lds((const unsigned*)((const char*)(gbase) + (voff)[_i]), (PG8_LAS unsigned*)(lds + (bufoff) + ldsw + _i * 8192), 16, 0, 0); } while (0)
; #define PG8_LDA(dst, b, h) do { _Pragma("unroll") for (int m = 0; m < 4; ++m) _Pragma("unroll") for (int k = 0; k < 2; ++k) dst[m][k] = *(const PG8_LAS bf16x8*)(lds + PG8_SA(b, h) + aoff + m * 2048 + k * 1024); } while (0)
; #define PG8_MMA(ai, bj, At, Bt) do { __builtin_amdgcn_s_setprio(1); _Pragma("unroll") for (int m = 0; m < 4; ++m) _Pragma("unroll") for (int n = 0; n < 2; ++n) _Pragma("unroll") for (int k = 0; k < 2; ++k) \
;         acc[ai][bj][m][n] = __builtin_amdgcn_mfma_f32_16x16x32_bf16(Bt[n][k], At[m][k], acc[ai][bj][m][n], 0, 0, 0); __builtin_amdgcn_s_setprio(0); } while (0)
; #define PG8_WAIT_V(n) asm volatile("s_waitcnt vmcnt(" #n ")" ::: "memory")
; #define PG8_WAIT_L(n) asm volatile("s_waitcnt lgkmcnt(" #n ")" ::: "memory")
; #define PG8_BAR __builtin_amdgcn_s_barrier()
; #define PG8_SCHED __builtin_amdgcn_sched_barrier(0)
; template <class Epi, class Sched, bool ALIGN_EPI = false, bool SP2 = false, bool KSEG = false>
; __device__ __forceinline__ void gemm_phase(PG8_LAS unsigned char* lds, const Gemm g, const Sched& S, const Epi& E) {
;     ...
;         for (int t = 0; t < nt; t += 2) {
;             const bool last = (t == nt - 2);
;             const char* a1 = cA + (size_t)(t + 1) * kstep;
;             const char* a2 = last ? nA : cA + (size_t)(t + 2) * kstep; const char* b2 = last ? nB : cB + (size_t)(t + 2) * kstep;
;             const char* a3 = a2 + kstep; const char* b3 = b2 + kstep;
;     ...
;             PG8_LDA(At, 1, 1); PG8_STAGE(PG8_SB(1, 0), b3, voffB); PG8_STAGE(PG8_SB(1, 1), b3 + hstep, voffB); PG8_STAGE(PG8_SA(1, 0), a3, voffA);
;             PG8_WAIT_V(8); PG8_WAIT_L(0); PG8_BAR; PG8_MMA(1, 0, At, B0); PG8_MMA(1, 1, At, B1); PG8_BAR; PG8_SCHED;
	s_add_i32 s28, s33, s30
	v_lshl_add_u64 v[216:217], v[216:217], 0, s[12:13]
	s_mov_b32 m0, s28
	ds_read_b128 v[184:187], v154 offset:49152
	ds_read_b128 v[188:191], v154 offset:50176
	ds_read_b128 v[192:195], v154 offset:51200
	ds_read_b128 v[196:199], v154 offset:52224
	ds_read_b128 v[200:203], v154 offset:53248
	ds_read_b128 v[204:207], v154 offset:54272
	ds_read_b128 v[208:211], v154 offset:55296
	ds_read_b128 v[212:215], v154 offset:56320
	global_load_lds_dwordx4 v[216:217], off
	s_add_i32 m0, s28, 0x2000
	s_add_u32 s26, s26, 0x160080
	v_lshl_add_u64 v[216:217], v[218:219], 0, s[12:13]
	s_addc_u32 s27, s27, 0
	s_add_i32 s28, s53, s30
	global_load_lds_dwordx4 v[216:217], off
	s_mov_b32 m0, s28
	v_lshl_add_u64 v[216:217], s[26:27], 0, v[130:131]
	global_load_lds_dwordx4 v[216:217], off
	s_add_i32 m0, s28, 0x2000
	v_lshl_add_u64 v[216:217], s[26:27], 0, v[144:145]
	global_load_lds_dwordx4 v[216:217], off
	s_waitcnt vmcnt(6) lgkmcnt(0)
	s_barrier
	s_setprio 1
	v_mfma_f32_16x16x32_bf16 v[62:65], v[146:149], v[184:187], v[62:65]
	v_mfma_f32_16x16x32_bf16 v[58:61], v[160:163], v[184:187], v[58:61]
	v_mfma_f32_16x16x32_bf16 v[46:49], v[146:149], v[192:195], v[46:49]
	v_mfma_f32_16x16x32_bf16 v[42:45], v[160:163], v[192:195], v[42:45]
	v_mfma_f32_16x16x32_bf16 v[30:33], v[146:149], v[200:203], v[30:33]
	v_mfma_f32_16x16x32_bf16 v[26:29], v[160:163], v[200:203], v[26:29]
	v_mfma_f32_16x16x32_bf16 v[14:17], v[146:149], v[208:211], v[14:17]
	v_mfma_f32_16x16x32_bf16 v[10:13], v[160:163], v[208:211], v[10:13]
	v_mfma_f32_16x16x32_bf16 v[62:65], v[156:159], v[188:191], v[62:65]
	v_mfma_f32_16x16x32_bf16 v[58:61], v[164:167], v[188:191], v[58:61]
	v_mfma_f32_16x16x32_bf16 v[46:49], v[156:159], v[196:199], v[46:49]
	v_mfma_f32_16x16x32_bf16 v[42:45], v[164:167], v[196:199], v[42:45]
	v_mfma_f32_16x16x32_bf16 v[30:33], v[156:159], v[204:207], v[30:33]
	v_mfma_f32_16x16x32_bf16 v[26:29], v[164:167], v[204:207], v[26:29]
	v_mfma_f32_16x16x32_bf16 v[14:17], v[156:159], v[212:215], v[14:17]
	v_mfma_f32_16x16x32_bf16 v[10:13], v[164:167], v[212:215], v[10:13]
	s_setprio 0
	s_setprio 1
	v_mfma_f32_16x16x32_bf16 v[54:57], v[168:171], v[184:187], v[54:57]
	s_add_i32 s50, s50, 2
	v_mfma_f32_16x16x32_bf16 v[50:53], v[176:179], v[184:187], v[50:53]
	s_add_u32 s24, s24, 0x100
	v_mfma_f32_16x16x32_bf16 v[38:41], v[168:171], v[192:195], v[38:41]
	s_addc_u32 s25, s25, 0
	v_mfma_f32_16x16x32_bf16 v[34:37], v[176:179], v[192:195], v[34:37]
	s_add_u32 s48, s48, 0x100
	v_mfma_f32_16x16x32_bf16 v[22:25], v[168:171], v[200:203], v[22:25]
	s_addc_u32 s49, s49, 0
	v_mfma_f32_16x16x32_bf16 v[18:21], v[176:179], v[200:203], v[18:21]
	s_add_u32 s26, s24, 0xffea0080
	v_mfma_f32_16x16x32_bf16 v[6:9], v[168:171], v[208:211], v[6:9]
	s_addc_u32 s27, s25, -1
	v_mfma_f32_16x16x32_bf16 v[2:5], v[176:179], v[208:211], v[2:5]
	s_cmpk_eq_i32 s50, 0x54
	v_mfma_f32_16x16x32_bf16 v[54:57], v[172:175], v[188:191], v[54:57]
	s_cselect_b32 s29, s21, s27
	v_mfma_f32_16x16x32_bf16 v[50:53], v[180:183], v[188:191], v[50:53]
	s_cselect_b32 s28, s20, s26
	v_mfma_f32_16x16x32_bf16 v[38:41], v[172:175], v[196:199], v[38:41]
	s_cselect_b32 s27, s9, s49
	v_mfma_f32_16x16x32_bf16 v[34:37], v[180:183], v[196:199], v[34:37]
	s_cselect_b32 s26, s8, s48
	v_mfma_f32_16x16x32_bf16 v[22:25], v[172:175], v[204:207], v[22:25]
	s_add_u32 s98, s24, 0xffea0000
	v_mfma_f32_16x16x32_bf16 v[18:21], v[180:183], v[204:207], v[18:21]
	s_addc_u32 s99, s25, -1
	v_mfma_f32_16x16x32_bf16 v[6:9], v[172:175], v[212:215], v[6:9]
	s_cmpk_lt_u32 s50, 0x56
	v_mfma_f32_16x16x32_bf16 v[2:5], v[180:183], v[212:215], v[2:5]
	s_setprio 0
	s_barrier
	s_cbranch_scc1 .LBB0_621
	s_andn2_b64 vcc, exec, s[18:19]
	s_cbranch_vccnz .LBB0_624
	s_barrier
